# SB tiles: half-wave exchange via v_permlane32_swap instead of ds_bpermute
# speedup vs baseline: 1.1081x; 1.0052x over previous
; DEV f32x16 mfma32(bf16x8 a, bf16x8 b, f32x16 c) { return __builtin_amdgcn_mfma_f32_32x32x16_bf16(a, b, c, 0, 0, 0); }
; template <bool DIAG>
; DEV void sb_tile(const char* lk, const char* lv, const int ko0, const int vo0, const bf16x8 (&qf)[8], f32x16 (&O)[4], float& accp,
;                  const int l31, const int hh) {
;   f32x16 z;
;   for (int g = 0; g < 16; ++g) z[g] = 0.f;
;   {
;     bf16x8 kf[8];
; #pragma unroll
;     for (int s = 0; s < 8; ++s) kf[s] = *(const bf16x8*)(lk + (ko0 ^ (32 * s)));
;     __builtin_amdgcn_sched_barrier(0);
; #pragma unroll
;     for (int s = 0; s < 8; ++s) z = mfma32(kf[s], qf[s], z);
;   }
;   bf16x8 vf[4][2];
; #pragma unroll
;   for (int d = 0; d < 4; ++d) { vf[d][0] = *(const bf16x8*)(lv + d * 4096 + vo0); vf[d][1] = *(const bf16x8*)(lv + d * 4096 + (vo0 ^ 32)); }
;   __builtin_amdgcn_sched_barrier(0);
;   float be[16], om[16];
; #pragma unroll
;   for (int g = 0; g < 16; ++g) {
;     const float e = __builtin_amdgcn_exp2f(fminf(-z[g], 120.f));
;     be[g] = __builtin_amdgcn_rcpf(1.f + e);
;     om[g] = e * be[g];
;     if (DIAG) { const int kl = (g & 3) + 8 * (g >> 2) + 4 * hh; if (kl >= l31) { be[g] = 0.f; om[g] = 1.f; } }
;   }
;   float gp[4], pp[4], tot[4];
; #pragma unroll
;   for (int q = 0; q < 4; ++q) { gp[q] = (om[4 * q] * om[4 * q + 1]) * (om[4 * q + 2] * om[4 * q + 3]); pp[q] = __shfl_xor(gp[q], 32); tot[q] = gp[q] * pp[q]; }
; DEV void sb_block(const Params& p, int item) {
;     ...
;     if (2 * j + 1 == qt) sb_tile<true>(lb_ + 32 * 256, lb_, ko0, vo0 ^ 64, qf, O, accp, l31, hh);
.LBB0_559:
	s_and_b32 s0, s33, 0x18000
	s_add_i32 s92, s0, 0
	s_add_i32 s0, s74, s69
	v_mov_b32_e32 v168, v205
	v_mov_b32_e32 v193, v206
	s_cmp_lg_u32 s89, s69
	s_mov_b64 s[66:67], -1
	s_cbranch_scc0 .LBB0_563
	s_add_i32 s1, s0, 7
	s_cmp_ge_i32 s1, s75
	s_cbranch_scc1 .Lsb_skip_A0
	v_add_u32_e32 v64, s92, v168
	v_xad_u32 v68, v168, 32, s92
	ds_read_b128 v[64:67], v64 offset:8192
	ds_read_b128 v[80:83], v68 offset:8192
	v_xad_u32 v68, v168, 64, s92
	v_xor_b32_e32 v69, 0x60, v168
	v_add_u32_e32 v69, s92, v69
	ds_read_b128 v[84:87], v68 offset:8192
	ds_read_b128 v[88:91], v69 offset:8192
	v_xor_b32_e32 v68, 0x80, v168
	v_add_u32_e32 v68, s92, v68
	v_xor_b32_e32 v69, 0xa0, v168
	v_add_u32_e32 v69, s92, v69
	ds_read_b128 v[92:95], v68 offset:8192
	ds_read_b128 v[96:99], v69 offset:8192
	v_xor_b32_e32 v68, 0xc0, v168
	v_add_u32_e32 v68, s92, v68
	v_xor_b32_e32 v69, 0xe0, v168
	v_add_u32_e32 v69, s92, v69
	ds_read_b128 v[100:103], v68 offset:8192
	ds_read_b128 v[104:107], v69 offset:8192
	s_waitcnt lgkmcnt(0)
	v_mfma_f32_32x32x16_bf16 v[64:79], v[64:67], v[128:131], 0
	v_mfma_f32_32x32x16_bf16 v[64:79], v[80:83], v[132:135], v[64:79]
	v_xor_b32_e32 v80, 0x60, v193
	v_mfma_f32_32x32x16_bf16 v[64:79], v[84:87], v[136:139], v[64:79]
	v_mfma_f32_32x32x16_bf16 v[64:79], v[88:91], v[140:143], v[64:79]
	v_xad_u32 v88, v193, 64, s92
	v_add_u32_e32 v89, s92, v80
	v_mfma_f32_32x32x16_bf16 v[64:79], v[92:95], v[144:147], v[64:79]
	v_mfma_f32_32x32x16_bf16 v[64:79], v[96:99], v[148:151], v[64:79]
	v_mfma_f32_32x32x16_bf16 v[64:79], v[100:103], v[152:155], v[64:79]
	ds_read_b128 v[84:87], v88
	ds_read_b128 v[96:99], v88 offset:4096
	ds_read_b128 v[80:83], v89
	ds_read_b128 v[100:103], v89 offset:4096
	ds_read_b128 v[112:115], v88 offset:8192
	ds_read_b128 v[164:167], v88 offset:12288
	ds_read_b128 v[116:119], v89 offset:8192
	ds_read_b128 v[160:163], v89 offset:12288
	v_mfma_f32_32x32x16_bf16 v[64:79], v[104:107], v[156:159], v[64:79]
	s_nop 11
	v_min_f32_e64 v68, -v68, s32
	v_exp_f32_e32 v90, v68
	v_min_f32_e64 v68, -v69, s32
	v_exp_f32_e32 v91, v68
	v_add_f32_e32 v68, 1.0, v90
	v_min_f32_e64 v73, -v73, s32
	v_add_f32_e32 v69, 1.0, v91
	v_rcp_f32_e32 v68, v68
	v_rcp_f32_e32 v69, v69
	v_exp_f32_e32 v104, v73
	v_max_f32_e64 v73, -v74, -v74
	v_max_f32_e64 v74, -v75, -v75
	v_min_f32_e64 v72, -v72, s32
	v_min_f32_e32 v74, 0x42f00000, v74
	v_min_f32_e64 v75, -v77, s32
	v_max_f32_e64 v77, -v79, -v79
	v_and_b32_e32 v79, 64, v219
	v_exp_f32_e32 v72, v72
	v_exp_f32_e32 v105, v74
	v_max_f32_e64 v74, -v76, -v76
	v_exp_f32_e32 v76, v75
	v_max_f32_e64 v75, -v78, -v78
	v_xor_b32_e32 v78, 32, v219
	v_add_u32_e32 v79, 64, v79
	v_min_f32_e32 v73, 0x42f00000, v73
	v_cmp_lt_i32_e32 vcc, v78, v79
	v_pk_mul_f32 v[90:91], v[90:91], v[68:69]
	v_exp_f32_e32 v73, v73
	v_cndmask_b32_e32 v78, v219, v78, vcc
	v_lshlrev_b32_e32 v170, 2, v78
	v_pk_mul_f32 v[78:79], v[90:91], v[90:91] op_sel_hi:[0,1]
	v_add_f32_e32 v78, 1.0, v72
	v_rcp_f32_e32 v108, v78
	v_add_f32_e32 v78, 1.0, v104
	v_rcp_f32_e32 v110, v78
	v_add_f32_e32 v78, 1.0, v73
	v_rcp_f32_e32 v109, v78
	v_add_f32_e32 v78, 1.0, v105
	v_min_f32_e32 v74, 0x42f00000, v74
	v_rcp_f32_e32 v111, v78
	v_exp_f32_e32 v74, v74
	v_min_f32_e32 v75, 0x42f00000, v75
	v_exp_f32_e32 v75, v75
	v_min_f32_e32 v77, 0x42f00000, v77
	v_exp_f32_e32 v77, v77
	v_pk_mul_f32 v[72:73], v[72:73], v[108:109]
	v_pk_mul_f32 v[104:105], v[104:105], v[110:111]
	v_pk_mul_f32 v[120:121], v[72:73], v[104:105]
	v_add_f32_e32 v72, 1.0, v74
	v_rcp_f32_e32 v122, v72
	v_add_f32_e32 v72, 1.0, v76
	v_rcp_f32_e32 v124, v72
	v_add_f32_e32 v72, 1.0, v75
	v_min_f32_e64 v70, -v70, s32
	v_rcp_f32_e32 v123, v72
	v_add_f32_e32 v72, 1.0, v77
	v_exp_f32_e32 v92, v70
	v_rcp_f32_e32 v125, v72
	v_min_f32_e64 v70, -v71, s32
	v_min_f32_e64 v67, -v67, s32
	v_exp_f32_e32 v93, v70
	v_min_f32_e64 v64, -v64, s32
	v_exp_f32_e32 v196, v67
	v_exp_f32_e32 v88, v64
	v_pk_mul_f32 v[74:75], v[74:75], v[122:123]
	v_pk_mul_f32 v[76:77], v[76:77], v[124:125]
	v_add_f32_e32 v70, 1.0, v92
	v_pk_mul_f32 v[126:127], v[74:75], v[76:77]
	v_add_f32_e32 v71, 1.0, v93
	v_mul_f32_e32 v72, v126, v127
	v_add_f32_e32 v67, 1.0, v196
	v_rcp_f32_e32 v70, v70
	v_rcp_f32_e32 v71, v71
	v_pk_mul_f32 v[120:121], v[120:121], v[120:121] op_sel:[0,1] op_sel_hi:[1,0]
	v_mov_b32_e32 v74, v72
	s_nop 1
	v_permlane32_swap_b32_e32 v72, v74
	v_add_f32_e32 v64, 1.0, v88
	v_min_f32_e64 v66, -v66, s32
	v_rcp_f32_e32 v67, v67
	v_mov_b32_e32 v121, v120
	s_nop 1
	v_permlane32_swap_b32_e32 v120, v121
	v_rcp_f32_e32 v64, v64
	v_min_f32_e64 v65, -v65, s32
	v_exp_f32_e32 v94, v66
	v_exp_f32_e32 v169, v65
	v_pk_mul_f32 v[92:93], v[92:93], v[70:71]
	s_waitcnt lgkmcnt(0)
; DEV f32x16 mfma32(bf16x8 a, bf16x8 b, f32x16 c) { return __builtin_amdgcn_mfma_f32_32x32x16_bf16(a, b, c, 0, 0, 0); }
; template <bool DIAG>
; DEV void sb_tile(const char* lk, const char* lv, const int ko0, const int vo0, const bf16x8 (&qf)[8], f32x16 (&O)[4], float& accp,
;                  const int l31, const int hh) {
;     ...
;   for (int q = 0; q < 4; ++q) { gp[q] = (om[4 * q] * om[4 * q + 1]) * (om[4 * q + 2] * om[4 * q + 3]); pp[q] = __shfl_xor(gp[q], 32); tot[q] = gp[q] * pp[q]; }
;   float suf[4];
;   suf[3] = accp; suf[2] = suf[3] * tot[3]; suf[1] = suf[2] * tot[2]; suf[0] = suf[1] * tot[1];
;   accp = suf[0] * tot[0];
;   f32x16 w;
; #pragma unroll
;   for (int q = 0; q < 4; ++q) {
;     float a = suf[q] * (hh == 0 ? pp[q] : 1.f);
;     w[4 * q + 3] = be[4 * q + 3] * a; a *= om[4 * q + 3];
;     w[4 * q + 2] = be[4 * q + 2] * a; a *= om[4 * q + 2];
;     w[4 * q + 1] = be[4 * q + 1] * a; a *= om[4 * q + 1];
;     w[4 * q + 0] = be[4 * q + 0] * a;
;   }
;   const bf16x8 w0 = cvt8<0>(w), w1 = cvt8<1>(w);
; #pragma unroll
;   for (int d = 0; d < 4; ++d) { O[d] = mfma32(vf[d][0], w0, O[d]); O[d] = mfma32(vf[d][1], w1, O[d]); }
	v_mul_f32_e32 v127, v72, v74
	v_pk_mul_f32 v[106:107], v[92:93], v[92:93] op_sel_hi:[0,1]
	v_mov_b32_e32 v126, v67
	v_add_f32_e32 v66, 1.0, v94
	v_mov_b32_e32 v89, v79
	v_cndmask_b32_e64 v72, 1.0, v121, s[10:11]
	v_mov_b32_e32 v78, v109
	v_mov_b32_e32 v79, v111
	v_mov_b32_e32 v109, v110
	v_pk_mul_f32 v[110:111], v[196:197], v[126:127]
	v_mov_b32_e32 v106, v64
	v_add_f32_e32 v65, 1.0, v169
	v_rcp_f32_e32 v66, v66
	v_mul_f32_e32 v127, v72, v111
	v_pk_mul_f32 v[88:89], v[88:89], v[106:107]
	v_rcp_f32_e32 v65, v65
	v_mul_f32_e32 v126, v105, v127
	v_mov_b32_e32 v105, v89
	s_nop 1
	v_permlane32_swap_b32_e32 v89, v105
	v_mov_b32_e32 v95, v120
	v_mov_b32_e32 v120, v66
	v_mul_f32_e32 v73, v73, v126
	v_pk_mul_f32 v[94:95], v[94:95], v[120:121]
	v_mul_f32_e32 v72, v104, v73
	v_mul_f32_e32 v104, v169, v65
	v_pk_mul_f32 v[120:121], v[94:95], v[110:111]
	s_waitcnt lgkmcnt(0)
	v_pk_mul_f32 v[88:89], v[88:89], v[104:105]
	v_cndmask_b32_e64 v90, 1.0, v105, s[10:11]
	v_pk_mul_f32 v[88:89], v[88:89], v[120:121]
	v_mov_b32_e32 v95, v88
	s_nop 1
	v_permlane32_swap_b32_e32 v88, v95
	v_cndmask_b32_e64 v74, 1.0, v74, s[10:11]
	v_pk_mul_f32 v[78:79], v[78:79], v[126:127]
	v_pk_mul_f32 v[72:73], v[108:109], v[72:73]
	v_cvt_pk_bf16_f32 v209, v78, v79
	s_waitcnt lgkmcnt(0)
	v_mul_f32_e32 v88, v88, v95
	v_mul_f32_e32 v199, v88, v89
	v_cndmask_b32_e64 v88, 1.0, v95, s[10:11]
	v_mul_f32_e32 v89, v88, v89
	v_mul_f32_e32 v88, v110, v89
	v_pk_mul_f32 v[66:67], v[66:67], v[88:89]
	v_mul_f32_e32 v89, v90, v121
	v_mul_f32_e32 v95, v94, v88
	v_mul_f32_e32 v88, v93, v89
	v_mul_f32_e32 v93, v92, v88
	v_mul_f32_e32 v92, v91, v93
	v_mul_f32_e32 v91, v197, v74
	v_mul_f32_e32 v90, v77, v91
	v_mul_f32_e32 v94, v104, v95
	v_mul_f32_e32 v75, v75, v90
	v_pk_mul_f32 v[64:65], v[64:65], v[94:95]
	v_pk_mul_f32 v[68:69], v[68:69], v[92:93]
	v_pk_mul_f32 v[70:71], v[70:71], v[88:89]
	v_mov_b32_e32 v88, v123
	v_mov_b32_e32 v123, v124
	v_mul_f32_e32 v74, v76, v75
	v_pk_mul_f32 v[74:75], v[122:123], v[74:75]
	v_cvt_pk_bf16_f32 v170, v64, v65
	v_cvt_pk_bf16_f32 v171, v66, v67
	v_cvt_pk_bf16_f32 v172, v68, v69
	v_cvt_pk_bf16_f32 v173, v70, v71
	v_cvt_pk_bf16_f32 v208, v72, v73
	v_cvt_pk_bf16_f32 v210, v74, v75
	v_mfma_f32_32x32x16_bf16 v[64:79], v[84:87], v[170:173], v[48:63]
	v_mov_b32_e32 v89, v125
	v_mul_f32_e64 v88, v88, v90
	v_mul_f32_e64 v89, v89, v91
	v_cvt_pk_bf16_f32 v211, v88, v89
	s_nop 1
	v_mfma_f32_32x32x16_bf16 v[64:79], v[80:83], v[208:211], v[64:79]
	v_mfma_f32_32x32x16_bf16 v[80:95], v[96:99], v[170:173], v[32:47]
	v_mfma_f32_32x32x16_bf16 v[80:95], v[100:103], v[208:211], v[80:95]
	v_mfma_f32_32x32x16_bf16 v[96:111], v[112:115], v[170:173], v[16:31]
	v_mfma_f32_32x32x16_bf16 v[96:111], v[116:119], v[208:211], v[96:111]
	v_mfma_f32_32x32x16_bf16 v[112:127], v[164:167], v[170:173], v[0:15]
	v_mfma_f32_32x32x16_bf16 v[112:127], v[160:163], v[208:211], v[112:127]

; DEV f32x16 mfma32(bf16x8 a, bf16x8 b, f32x16 c) { return __builtin_amdgcn_mfma_f32_32x32x16_bf16(a, b, c, 0, 0, 0); }
; template <bool DIAG>
; DEV void sb_tile(const char* lk, const char* lv, const int ko0, const int vo0, const bf16x8 (&qf)[8], f32x16 (&O)[4], float& accp,
;                  const int l31, const int hh) {
;   f32x16 z;
;   for (int g = 0; g < 16; ++g) z[g] = 0.f;
;   {
;     bf16x8 kf[8];
; #pragma unroll
;     for (int s = 0; s < 8; ++s) kf[s] = *(const bf16x8*)(lk + (ko0 ^ (32 * s)));
;     __builtin_amdgcn_sched_barrier(0);
; #pragma unroll
;     for (int s = 0; s < 8; ++s) z = mfma32(kf[s], qf[s], z);
;   }
;   bf16x8 vf[4][2];
; #pragma unroll
;   for (int d = 0; d < 4; ++d) { vf[d][0] = *(const bf16x8*)(lv + d * 4096 + vo0); vf[d][1] = *(const bf16x8*)(lv + d * 4096 + (vo0 ^ 32)); }
;   __builtin_amdgcn_sched_barrier(0);
;   float be[16], om[16];
; #pragma unroll
;   for (int g = 0; g < 16; ++g) {
;     const float e = __builtin_amdgcn_exp2f(fminf(-z[g], 120.f));
;     be[g] = __builtin_amdgcn_rcpf(1.f + e);
;     om[g] = e * be[g];
;     if (DIAG) { const int kl = (g & 3) + 8 * (g >> 2) + 4 * hh; if (kl >= l31) { be[g] = 0.f; om[g] = 1.f; } }
;   }
;   float gp[4], pp[4], tot[4];
; #pragma unroll
;   for (int q = 0; q < 4; ++q) { gp[q] = (om[4 * q] * om[4 * q + 1]) * (om[4 * q + 2] * om[4 * q + 3]); pp[q] = __shfl_xor(gp[q], 32); tot[q] = gp[q] * pp[q]; }
; DEV void sb_block(const Params& p, int item) {
;     ...
;     if (2 * j + 1 == qt) sb_tile<true>(lb_ + 32 * 256, lb_, ko0, vo0 ^ 64, qf, O, accp, l31, hh);
.LBB0_563:
	v_xor_b32_e32 v160, 0x60, v168
	v_xor_b32_e32 v161, 0x80, v168
	v_xor_b32_e32 v162, 0xa0, v168
	v_xor_b32_e32 v163, 0xc0, v168
	v_xor_b32_e32 v164, 0xe0, v168
	s_andn2_b64 vcc, exec, s[66:67]
	v_add_u32_e32 v195, s92, v168
	v_xad_u32 v196, v168, 32, s92
	v_xad_u32 v207, v168, 64, s92
	v_add_u32_e32 v208, s92, v160
	v_add_u32_e32 v209, s92, v161
	v_add_u32_e32 v210, s92, v162
	v_add_u32_e32 v211, s92, v163
	v_add_u32_e32 v212, s92, v164
	s_cbranch_vccnz .LBB0_565
	ds_read_b128 v[64:67], v195 offset:8192
	ds_read_b128 v[80:83], v196 offset:8192
	ds_read_b128 v[84:87], v207 offset:8192
	ds_read_b128 v[88:91], v208 offset:8192
	ds_read_b128 v[92:95], v209 offset:8192
	ds_read_b128 v[96:99], v210 offset:8192
	ds_read_b128 v[100:103], v211 offset:8192
	ds_read_b128 v[112:115], v212 offset:8192
	s_waitcnt lgkmcnt(0)
	v_mfma_f32_32x32x16_bf16 v[64:79], v[64:67], v[128:131], 0
	v_mfma_f32_32x32x16_bf16 v[64:79], v[80:83], v[132:135], v[64:79]
	v_xor_b32_e32 v80, 0x60, v193
	v_xad_u32 v81, v193, 64, s92
	v_add_u32_e32 v80, s92, v80
	v_mfma_f32_32x32x16_bf16 v[64:79], v[84:87], v[136:139], v[64:79]
	v_mfma_f32_32x32x16_bf16 v[64:79], v[88:91], v[140:143], v[64:79]
	v_mfma_f32_32x32x16_bf16 v[64:79], v[92:95], v[144:147], v[64:79]
	v_mfma_f32_32x32x16_bf16 v[64:79], v[96:99], v[148:151], v[64:79]
	v_mfma_f32_32x32x16_bf16 v[64:79], v[100:103], v[152:155], v[64:79]
	ds_read_b128 v[108:111], v81
	ds_read_b128 v[96:99], v81 offset:4096
	ds_read_b128 v[104:107], v80
	ds_read_b128 v[100:103], v80 offset:4096
	ds_read_b128 v[88:91], v81 offset:8192
	ds_read_b128 v[84:87], v81 offset:12288
	ds_read_b128 v[92:95], v80 offset:8192
	ds_read_b128 v[80:83], v80 offset:12288
	v_mfma_f32_32x32x16_bf16 v[64:79], v[112:115], v[156:159], v[64:79]
	s_nop 11
	v_min_f32_e64 v64, -v64, s32
	v_exp_f32_e32 v64, v64
	v_min_f32_e64 v65, -v65, s32
	v_exp_f32_e32 v65, v65
	v_add_f32_e32 v112, 1.0, v64
	v_rcp_f32_e32 v120, v112
	v_add_f32_e32 v112, 1.0, v65
	v_min_f32_e64 v66, -v66, s32
	v_rcp_f32_e32 v121, v112
	v_exp_f32_e32 v112, v66
	v_min_f32_e64 v66, -v67, s32
	v_exp_f32_e32 v67, v66
	v_add_f32_e32 v66, 1.0, v112
	v_rcp_f32_e32 v122, v66
	v_mul_f32_e32 v65, v65, v121
	v_add_f32_e32 v66, 1.0, v67
	v_rcp_f32_e32 v123, v66
	v_cndmask_b32_e64 v66, 1.0, v65, s[14:15]
	v_mul_f32_e32 v65, v112, v122
	v_cndmask_b32_e64 v112, 1.0, v65, s[16:17]
	v_mul_f32_e32 v65, v67, v123
	v_min_f32_e64 v67, -v68, s32
	v_exp_f32_e32 v67, v67
	v_min_f32_e64 v68, -v69, s32
	v_exp_f32_e32 v69, v68
	v_cndmask_b32_e64 v68, 1.0, v65, s[18:19]
	v_add_f32_e32 v65, 1.0, v67
	v_rcp_f32_e32 v124, v65
	v_add_f32_e32 v65, 1.0, v69
	v_rcp_f32_e32 v125, v65
	v_min_f32_e64 v65, -v70, s32
	v_exp_f32_e32 v65, v65
	v_mul_f32_e32 v67, v67, v124
	v_cndmask_b32_e64 v70, 1.0, v67, s[20:21]
	v_mul_f32_e32 v67, v69, v125
	v_add_f32_e32 v69, 1.0, v65
	v_rcp_f32_e32 v126, v69
	v_min_f32_e64 v69, -v71, s32
	v_exp_f32_e32 v69, v69
	v_mul_f32_e32 v65, v65, v126
	v_cndmask_b32_e64 v115, 1.0, v65, s[24:25]
	v_cndmask_b32_e64 v114, 1.0, v67, s[22:23]
	v_add_f32_e32 v65, 1.0, v69
	v_rcp_f32_e32 v127, v65
	v_min_f32_e64 v65, -v72, s32
	v_exp_f32_e32 v65, v65
	v_min_f32_e64 v67, -v73, s32
	v_exp_f32_e32 v67, v67
	v_mul_f32_e32 v69, v69, v127
	v_add_f32_e32 v71, 1.0, v65
	v_rcp_f32_e32 v160, v71
	v_add_f32_e32 v71, 1.0, v67
	v_rcp_f32_e32 v161, v71
	v_cndmask_b32_e64 v71, 1.0, v69, s[26:27]
	v_mul_f32_e32 v65, v65, v160
	v_cndmask_b32_e64 v72, 1.0, v65, s[28:29]
	v_mul_f32_e32 v65, v67, v161
	v_min_f32_e64 v67, -v74, s32
	v_exp_f32_e32 v67, v67
	v_min_f32_e64 v69, -v75, s32
	v_exp_f32_e32 v69, v69
	v_cndmask_b32_e64 v74, 1.0, v65, s[30:31]
	v_add_f32_e32 v65, 1.0, v67
	v_rcp_f32_e32 v162, v65
	v_add_f32_e32 v65, 1.0, v69
	v_rcp_f32_e32 v163, v65
	v_min_f32_e64 v65, -v76, s32
	v_exp_f32_e32 v65, v65
	v_mul_f32_e32 v67, v67, v162
	v_cndmask_b32_e64 v75, 1.0, v67, s[34:35]
	v_mul_f32_e32 v67, v69, v163
	v_add_f32_e32 v69, 1.0, v65
	v_rcp_f32_e32 v164, v69
	v_min_f32_e64 v69, -v77, s32
	v_exp_f32_e32 v69, v69
	v_mul_f32_e32 v65, v65, v164
	v_cndmask_b32_e64 v76, 1.0, v65, s[38:39]
	v_cndmask_b32_e64 v73, 1.0, v67, s[36:37]
	v_add_f32_e32 v65, 1.0, v69
	v_rcp_f32_e32 v165, v65
	v_min_f32_e64 v65, -v78, s32
	v_exp_f32_e32 v65, v65
	v_min_f32_e64 v67, -v79, s32
	v_exp_f32_e32 v67, v67
	v_mul_f32_e32 v69, v69, v165
	v_add_f32_e32 v77, 1.0, v65
	v_rcp_f32_e32 v166, v77
	v_add_f32_e32 v77, 1.0, v67
	v_rcp_f32_e32 v167, v77
	v_cndmask_b32_e64 v78, 1.0, v69, s[40:41]
	v_mul_f32_e32 v65, v65, v166
	v_cndmask_b32_e64 v79, 1.0, v65, s[42:43]
	v_mul_f32_e32 v65, v67, v167
	v_and_b32_e32 v67, 64, v219
	v_cndmask_b32_e64 v77, 1.0, v65, s[44:45]
	v_xor_b32_e32 v65, 32, v219
	v_add_u32_e32 v67, 64, v67
	v_cmp_lt_i32_e32 vcc, v65, v67
	v_pk_mul_f32 v[116:117], v[74:75], v[72:73]
	v_mul_f32_e32 v64, v64, v120
	v_cndmask_b32_e32 v65, v219, v65, vcc
	v_lshlrev_b32_e32 v168, 2, v65
	v_mul_f32_e32 v65, v116, v117
	v_pk_mul_f32 v[116:117], v[78:79], v[76:77]
	v_mov_b32_e32 v72, v65
	s_nop 1
	v_permlane32_swap_b32_e32 v65, v72
	v_mul_f32_e32 v69, v116, v117
	v_mov_b32_e32 v76, v69
	s_nop 1
	v_permlane32_swap_b32_e32 v69, v76
	v_pk_mul_f32 v[116:117], v[114:115], v[70:71]
	v_cndmask_b32_e64 v64, 1.0, v64, s[12:13]
	v_pk_mul_f32 v[116:117], v[116:117], v[116:117] op_sel:[0,1] op_sel_hi:[1,0]
	v_mov_b32_e32 v67, v116
	s_nop 1
	v_permlane32_swap_b32_e32 v116, v67
	s_waitcnt lgkmcnt(0)
; DEV f32x16 mfma32(bf16x8 a, bf16x8 b, f32x16 c) { return __builtin_amdgcn_mfma_f32_32x32x16_bf16(a, b, c, 0, 0, 0); }
; template <bool DIAG>
; DEV void sb_tile(const char* lk, const char* lv, const int ko0, const int vo0, const bf16x8 (&qf)[8], f32x16 (&O)[4], float& accp,
;                  const int l31, const int hh) {
;     ...
;   for (int q = 0; q < 4; ++q) { gp[q] = (om[4 * q] * om[4 * q + 1]) * (om[4 * q + 2] * om[4 * q + 3]); pp[q] = __shfl_xor(gp[q], 32); tot[q] = gp[q] * pp[q]; }
;   float suf[4];
;   suf[3] = accp; suf[2] = suf[3] * tot[3]; suf[1] = suf[2] * tot[2]; suf[0] = suf[1] * tot[1];
;   accp = suf[0] * tot[0];
;   f32x16 w;
; #pragma unroll
;   for (int q = 0; q < 4; ++q) {
;     float a = suf[q] * (hh == 0 ? pp[q] : 1.f);
;     w[4 * q + 3] = be[4 * q + 3] * a; a *= om[4 * q + 3];
;     w[4 * q + 2] = be[4 * q + 2] * a; a *= om[4 * q + 2];
;     w[4 * q + 1] = be[4 * q + 1] * a; a *= om[4 * q + 1];
;     w[4 * q + 0] = be[4 * q + 0] * a;
;   }
;   const bf16x8 w0 = cvt8<0>(w), w1 = cvt8<1>(w);
; #pragma unroll
;   for (int d = 0; d < 4; ++d) { O[d] = mfma32(vf[d][0], w0, O[d]); O[d] = mfma32(vf[d][1], w1, O[d]); }
	v_mul_f32_e32 v113, v65, v72
	v_mul_f32_e32 v65, v69, v76
	v_mul_f32_e32 v69, v197, v65
	v_mov_b32_e32 v65, v116
	v_pk_mul_f32 v[64:65], v[64:65], v[66:67]
	v_pk_mul_f32 v[116:117], v[112:113], v[68:69]
	v_cndmask_b32_e64 v113, 1.0, v67, s[10:11]
	v_pk_mul_f32 v[118:119], v[64:65], v[116:117]
	v_mov_b32_e32 v116, v118
	s_nop 1
	v_permlane32_swap_b32_e32 v118, v116
	v_cndmask_b32_e64 v67, 1.0, v72, s[10:11]
	v_cndmask_b32_e64 v65, 0, v121, s[14:15]
	v_cndmask_b32_e64 v121, 0, v123, s[18:19]
	v_cndmask_b32_e64 v123, 0, v125, s[22:23]
	s_waitcnt lgkmcnt(0)
	v_cndmask_b32_e64 v70, 1.0, v116, s[10:11]
	v_cndmask_b32_e64 v125, 0, v127, s[26:27]
	v_cndmask_b32_e64 v127, 0, v161, s[30:31]
	v_cndmask_b32_e64 v161, 0, v163, s[36:37]
	v_cndmask_b32_e64 v163, 0, v165, s[40:41]
	v_cndmask_b32_e64 v165, 0, v167, s[44:45]
	v_mul_f32_e32 v167, v67, v69
	v_mul_f32_e32 v69, v70, v119
	v_mul_f32_e32 v68, v68, v69
	v_mul_f32_e32 v67, v112, v68
	v_cndmask_b32_e64 v64, 0, v120, s[12:13]
	v_cndmask_b32_e64 v120, 0, v122, s[16:17]
	v_mul_f32_e32 v66, v66, v67
	v_pk_mul_f32 v[64:65], v[64:65], v[66:67]
	v_pk_mul_f32 v[66:67], v[120:121], v[68:69]
	v_mul_f32_e32 v69, v113, v117
	v_mul_f32_e32 v68, v71, v69
	v_mul_f32_e32 v71, v115, v68
	v_cndmask_b32_e64 v122, 0, v124, s[20:21]
	v_cndmask_b32_e64 v124, 0, v126, s[24:25]
	v_mul_f32_e32 v70, v114, v71
	v_pk_mul_f32 v[70:71], v[122:123], v[70:71]
	v_pk_mul_f32 v[68:69], v[124:125], v[68:69]
	v_cvt_pk_bf16_f32 v64, v64, v65
	v_cvt_pk_bf16_f32 v65, v66, v67
	v_cvt_pk_bf16_f32 v66, v70, v71
	v_cvt_pk_bf16_f32 v67, v68, v69
	v_cndmask_b32_e64 v76, 1.0, v76, s[10:11]
	v_mul_f32_e32 v113, v197, v76
	v_mfma_f32_32x32x16_bf16 v[48:63], v[108:111], v[64:67], v[48:63]
	v_cndmask_b32_e64 v126, 0, v160, s[28:29]
	v_cndmask_b32_e64 v160, 0, v162, s[34:35]
	v_cndmask_b32_e64 v162, 0, v164, s[38:39]
	v_cndmask_b32_e64 v164, 0, v166, s[42:43]
	v_mul_f32_e32 v166, v73, v167
	v_mul_f32_e32 v112, v113, v77
	v_mul_f32_e32 v75, v75, v166
	v_mfma_f32_32x32x16_bf16 v[32:47], v[96:99], v[64:67], v[32:47]
	v_mul_f32_e32 v69, v79, v112
	v_mul_f32_e32 v74, v74, v75
	v_mul_f32_e32 v68, v78, v69
	v_mul_f32_e64 v72, v160, v166
	v_mul_f32_e64 v73, v161, v167
	v_pk_mul_f32 v[74:75], v[126:127], v[74:75]
	v_pk_mul_f32 v[76:77], v[164:165], v[112:113]
	v_pk_mul_f32 v[70:71], v[162:163], v[68:69]
	v_mfma_f32_32x32x16_bf16 v[16:31], v[88:91], v[64:67], v[16:31]
	v_cvt_pk_bf16_f32 v68, v74, v75
	v_cvt_pk_bf16_f32 v69, v72, v73
	v_cvt_pk_bf16_f32 v70, v70, v71
	v_cvt_pk_bf16_f32 v71, v76, v77
	v_mfma_f32_32x32x16_bf16 v[0:15], v[84:87], v[64:67], v[0:15]
	v_mul_f32_e32 v64, v118, v116
	v_mul_f32_e32 v199, v64, v119
	v_mfma_f32_32x32x16_bf16 v[48:63], v[104:107], v[68:71], v[48:63]
	v_mfma_f32_32x32x16_bf16 v[32:47], v[100:103], v[68:71], v[32:47]
	v_mfma_f32_32x32x16_bf16 v[16:31], v[92:95], v[68:71], v[16:31]
	v_mfma_f32_32x32x16_bf16 v[0:15], v[80:83], v[68:71], v[0:15]
	s_nop 10
	v_mov_b64_e32 v[110:111], v[30:31]
	v_mov_b64_e32 v[94:95], v[46:47]
	v_mov_b64_e32 v[78:79], v[62:63]
	v_mov_b64_e32 v[108:109], v[28:29]
	v_mov_b64_e32 v[106:107], v[26:27]
	v_mov_b64_e32 v[104:105], v[24:25]
	v_mov_b64_e32 v[102:103], v[22:23]
	v_mov_b64_e32 v[126:127], v[14:15]
	v_mov_b64_e32 v[124:125], v[12:13]
	v_mov_b64_e32 v[122:123], v[10:11]
	v_mov_b64_e32 v[120:121], v[8:9]
	v_mov_b64_e32 v[118:119], v[6:7]
	v_mov_b64_e32 v[116:117], v[4:5]
	v_mov_b64_e32 v[114:115], v[2:3]
	v_mov_b64_e32 v[112:113], v[0:1]
	v_mov_b64_e32 v[100:101], v[20:21]
	v_mov_b64_e32 v[98:99], v[18:19]
	v_mov_b64_e32 v[96:97], v[16:17]
	v_mov_b64_e32 v[92:93], v[44:45]
	v_mov_b64_e32 v[90:91], v[42:43]
	v_mov_b64_e32 v[88:89], v[40:41]
	v_mov_b64_e32 v[86:87], v[38:39]
	v_mov_b64_e32 v[84:85], v[36:37]
	v_mov_b64_e32 v[82:83], v[34:35]
	v_mov_b64_e32 v[80:81], v[32:33]
	v_mov_b64_e32 v[76:77], v[60:61]
	v_mov_b64_e32 v[74:75], v[58:59]
	v_mov_b64_e32 v[72:73], v[56:57]
	v_mov_b64_e32 v[70:71], v[54:55]
	v_mov_b64_e32 v[68:69], v[52:53]
	v_mov_b64_e32 v[66:67], v[50:51]
	v_mov_b64_e32 v[64:65], v[48:49]
; DEV f32x16 mfma32(bf16x8 a, bf16x8 b, f32x16 c) { return __builtin_amdgcn_mfma_f32_32x32x16_bf16(a, b, c, 0, 0, 0); }
; template <bool DIAG>
; DEV void sb_tile(const char* lk, const char* lv, const int ko0, const int vo0, const bf16x8 (&qf)[8], f32x16 (&O)[4], float& accp,
;                  const int l31, const int hh) {
;   f32x16 z;
;   for (int g = 0; g < 16; ++g) z[g] = 0.f;
;   {
;     bf16x8 kf[8];
; #pragma unroll
;     for (int s = 0; s < 8; ++s) kf[s] = *(const bf16x8*)(lk + (ko0 ^ (32 * s)));
;     __builtin_amdgcn_sched_barrier(0);
; #pragma unroll
;     for (int s = 0; s < 8; ++s) z = mfma32(kf[s], qf[s], z);
;   }
;   bf16x8 vf[4][2];
; #pragma unroll
;   for (int d = 0; d < 4; ++d) { vf[d][0] = *(const bf16x8*)(lv + d * 4096 + vo0); vf[d][1] = *(const bf16x8*)(lv + d * 4096 + (vo0 ^ 32)); }
;   __builtin_amdgcn_sched_barrier(0);
;   float be[16], om[16];
; #pragma unroll
;   for (int g = 0; g < 16; ++g) {
;     const float e = __builtin_amdgcn_exp2f(fminf(-z[g], 120.f));
;     be[g] = __builtin_amdgcn_rcpf(1.f + e);
;     om[g] = e * be[g];
;     if (DIAG) { const int kl = (g & 3) + 8 * (g >> 2) + 4 * hh; if (kl >= l31) { be[g] = 0.f; om[g] = 1.f; } }
;   }
;   float gp[4], pp[4], tot[4];
; #pragma unroll
;   for (int q = 0; q < 4; ++q) { gp[q] = (om[4 * q] * om[4 * q + 1]) * (om[4 * q + 2] * om[4 * q + 3]); pp[q] = __shfl_xor(gp[q], 32); tot[q] = gp[q] * pp[q]; }
;   float suf[4];
;   suf[3] = accp; suf[2] = suf[3] * tot[3]; suf[1] = suf[2] * tot[2]; suf[0] = suf[1] * tot[1];
;   accp = suf[0] * tot[0];
;   f32x16 w;
; #pragma unroll
;   for (int q = 0; q < 4; ++q) {
;     float a = suf[q] * (hh == 0 ? pp[q] : 1.f);
;     w[4 * q + 3] = be[4 * q + 3] * a; a *= om[4 * q + 3];
;     w[4 * q + 2] = be[4 * q + 2] * a; a *= om[4 * q + 2];
;     w[4 * q + 1] = be[4 * q + 1] * a; a *= om[4 * q + 1];
;     w[4 * q + 0] = be[4 * q + 0] * a;
;   }
;   const bf16x8 w0 = cvt8<0>(w), w1 = cvt8<1>(w);
; #pragma unroll
;   for (int d = 0; d < 4; ++d) { O[d] = mfma32(vf[d][0], w0, O[d]); O[d] = mfma32(vf[d][1], w1, O[d]); }
; DEV void sb_block(const Params& p, int item) {
;     ...
;     else if (2 * j < qt) sb_tile<false>(lb_, lb_, ko0, vo0, qf, O, accp, l31, hh);
.LBB0_565:
	s_cmp_lg_u32 s88, s69
	s_mov_b64 s[66:67], -1
	s_cbranch_scc0 .LBB0_569
	s_add_i32 s0, s0, 6
	s_cmp_ge_i32 s0, s75
	s_cbranch_scc1 .Lsb_skip_B0
	ds_read_b128 v[0:3], v195
	ds_read_b128 v[16:19], v196
	ds_read_b128 v[20:23], v207
	ds_read_b128 v[24:27], v208
	ds_read_b128 v[28:31], v209
	ds_read_b128 v[32:35], v210
	ds_read_b128 v[36:39], v211
	ds_read_b128 v[40:43], v212
	s_waitcnt lgkmcnt(0)
	v_mfma_f32_32x32x16_bf16 v[0:15], v[0:3], v[128:131], 0
	v_mfma_f32_32x32x16_bf16 v[0:15], v[16:19], v[132:135], v[0:15]
	v_mfma_f32_32x32x16_bf16 v[0:15], v[20:23], v[136:139], v[0:15]
	v_mfma_f32_32x32x16_bf16 v[0:15], v[24:27], v[140:143], v[0:15]
	v_mfma_f32_32x32x16_bf16 v[0:15], v[28:31], v[144:147], v[0:15]
	v_mfma_f32_32x32x16_bf16 v[0:15], v[32:35], v[148:151], v[0:15]
	v_add_u32_e32 v32, s92, v193
	v_xad_u32 v33, v193, 32, s92
	ds_read_b128 v[28:31], v32
	ds_read_b128 v[16:19], v32 offset:4096
	ds_read_b128 v[24:27], v33
	ds_read_b128 v[20:23], v33 offset:4096
	ds_read_b128 v[168:171], v32 offset:8192
	ds_read_b128 v[164:167], v32 offset:12288
	ds_read_b128 v[172:175], v33 offset:8192
	ds_read_b128 v[160:163], v33 offset:12288
	v_mfma_f32_32x32x16_bf16 v[0:15], v[36:39], v[152:155], v[0:15]
	v_mfma_f32_32x32x16_bf16 v[0:15], v[40:43], v[156:159], v[0:15]
	s_nop 11
	v_min_f32_e64 v4, -v4, s32
	v_exp_f32_e32 v34, v4
	v_min_f32_e64 v4, -v5, s32
	v_exp_f32_e32 v35, v4
	v_add_f32_e32 v4, 1.0, v34
	v_min_f32_e64 v9, -v9, s32
	v_add_f32_e32 v5, 1.0, v35
	v_rcp_f32_e32 v4, v4
	v_rcp_f32_e32 v5, v5
	v_exp_f32_e32 v40, v9
	v_max_f32_e64 v9, -v10, -v10
	v_max_f32_e64 v10, -v11, -v11
	v_min_f32_e64 v8, -v8, s32
	v_min_f32_e32 v10, 0x42f00000, v10
	v_min_f32_e64 v11, -v13, s32
	v_max_f32_e64 v13, -v15, -v15
	v_and_b32_e32 v15, 64, v219
	v_exp_f32_e32 v8, v8
	v_exp_f32_e32 v41, v10
	v_max_f32_e64 v10, -v12, -v12
	v_exp_f32_e32 v12, v11
	v_max_f32_e64 v11, -v14, -v14
	v_xor_b32_e32 v14, 32, v219
	v_add_u32_e32 v15, 64, v15
	v_min_f32_e32 v9, 0x42f00000, v9
	v_cmp_lt_i32_e32 vcc, v14, v15
	v_pk_mul_f32 v[34:35], v[34:35], v[4:5]
	v_exp_f32_e32 v9, v9
	v_cndmask_b32_e32 v14, v219, v14, vcc
	v_lshlrev_b32_e32 v57, 2, v14
	v_pk_mul_f32 v[14:15], v[34:35], v[34:35] op_sel_hi:[0,1]
	v_add_f32_e32 v14, 1.0, v8
	v_rcp_f32_e32 v44, v14
	v_add_f32_e32 v14, 1.0, v40
	v_rcp_f32_e32 v46, v14
	v_add_f32_e32 v14, 1.0, v9
	v_rcp_f32_e32 v45, v14
	v_add_f32_e32 v14, 1.0, v41
	v_min_f32_e32 v10, 0x42f00000, v10
	v_rcp_f32_e32 v47, v14
	v_exp_f32_e32 v10, v10
	v_min_f32_e32 v11, 0x42f00000, v11
	v_exp_f32_e32 v11, v11
	v_min_f32_e32 v13, 0x42f00000, v13
	v_exp_f32_e32 v13, v13
	v_pk_mul_f32 v[8:9], v[8:9], v[44:45]
	v_pk_mul_f32 v[40:41], v[40:41], v[46:47]
	v_pk_mul_f32 v[48:49], v[8:9], v[40:41]
	v_add_f32_e32 v8, 1.0, v10
	v_rcp_f32_e32 v50, v8
	v_add_f32_e32 v8, 1.0, v12
	v_rcp_f32_e32 v52, v8
	v_add_f32_e32 v8, 1.0, v11
	v_min_f32_e64 v6, -v6, s32
	v_rcp_f32_e32 v51, v8
	v_add_f32_e32 v8, 1.0, v13
	v_exp_f32_e32 v36, v6
	v_rcp_f32_e32 v53, v8
	v_min_f32_e64 v6, -v7, s32
	v_min_f32_e64 v3, -v3, s32
	v_exp_f32_e32 v37, v6
	v_min_f32_e64 v0, -v0, s32
	v_exp_f32_e32 v198, v3
	v_exp_f32_e32 v32, v0
	v_pk_mul_f32 v[10:11], v[10:11], v[50:51]
	v_pk_mul_f32 v[12:13], v[12:13], v[52:53]
	v_add_f32_e32 v6, 1.0, v36
	v_pk_mul_f32 v[54:55], v[10:11], v[12:13]
	v_add_f32_e32 v7, 1.0, v37
	v_mul_f32_e32 v8, v54, v55
	v_add_f32_e32 v3, 1.0, v198
	v_rcp_f32_e32 v6, v6
	v_rcp_f32_e32 v7, v7
	v_pk_mul_f32 v[48:49], v[48:49], v[48:49] op_sel:[0,1] op_sel_hi:[1,0]
	v_mov_b32_e32 v10, v8
	s_nop 1
	v_permlane32_swap_b32_e32 v8, v10
	v_add_f32_e32 v0, 1.0, v32
	v_min_f32_e64 v2, -v2, s32
	v_rcp_f32_e32 v3, v3
	v_mov_b32_e32 v49, v48
	s_nop 1
	v_permlane32_swap_b32_e32 v48, v49
	v_rcp_f32_e32 v0, v0
	v_min_f32_e64 v1, -v1, s32
	v_exp_f32_e32 v38, v2
	v_exp_f32_e32 v56, v1
	v_pk_mul_f32 v[36:37], v[36:37], v[6:7]
	s_waitcnt lgkmcnt(0)
	v_mul_f32_e32 v55, v8, v10
	v_pk_mul_f32 v[42:43], v[36:37], v[36:37] op_sel_hi:[0,1]
	v_mov_b32_e32 v54, v3
	v_add_f32_e32 v2, 1.0, v38
	v_mov_b32_e32 v33, v15
	v_cndmask_b32_e64 v8, 1.0, v49, s[10:11]
	v_mov_b32_e32 v14, v45
	v_mov_b32_e32 v15, v47
	v_mov_b32_e32 v45, v46
	v_pk_mul_f32 v[46:47], v[198:199], v[54:55]
	v_mov_b32_e32 v42, v0
	v_add_f32_e32 v1, 1.0, v56
	v_rcp_f32_e32 v2, v2
	v_mul_f32_e32 v55, v8, v47
	v_pk_mul_f32 v[32:33], v[32:33], v[42:43]
	v_rcp_f32_e32 v1, v1
	v_mul_f32_e32 v54, v41, v55
	v_mov_b32_e32 v41, v33
	s_nop 1
	v_permlane32_swap_b32_e32 v33, v41
	v_mov_b32_e32 v39, v48
	v_mov_b32_e32 v48, v2
	v_mul_f32_e32 v9, v9, v54
	v_pk_mul_f32 v[38:39], v[38:39], v[48:49]
	v_mul_f32_e32 v8, v40, v9
	v_mul_f32_e32 v40, v56, v1
	v_pk_mul_f32 v[48:49], v[38:39], v[46:47]
	s_waitcnt lgkmcnt(0)
	v_pk_mul_f32 v[32:33], v[32:33], v[40:41]
	v_cndmask_b32_e64 v34, 1.0, v41, s[10:11]
	v_pk_mul_f32 v[32:33], v[32:33], v[48:49]
	v_mov_b32_e32 v39, v32
	s_nop 1
	v_permlane32_swap_b32_e32 v32, v39
	v_cndmask_b32_e64 v10, 1.0, v10, s[10:11]
	v_pk_mul_f32 v[14:15], v[14:15], v[54:55]
	v_pk_mul_f32 v[8:9], v[44:45], v[8:9]
	v_cvt_pk_bf16_f32 v225, v14, v15
	s_waitcnt lgkmcnt(0)
	v_mul_f32_e32 v32, v32, v39
	v_mul_f32_e32 v197, v32, v33
	v_cndmask_b32_e64 v32, 1.0, v39, s[10:11]
	v_mul_f32_e32 v33, v32, v33
	v_mul_f32_e32 v32, v46, v33
	v_pk_mul_f32 v[2:3], v[2:3], v[32:33]
	v_mul_f32_e32 v33, v34, v49
	v_mul_f32_e32 v39, v38, v32
	v_mul_f32_e32 v32, v37, v33
	v_mul_f32_e32 v37, v36, v32
	v_mul_f32_e32 v36, v35, v37
	v_mul_f32_e32 v35, v199, v10
	v_mul_f32_e32 v38, v40, v39
	v_mul_f32_e32 v34, v13, v35
	v_pk_mul_f32 v[0:1], v[0:1], v[38:39]
	v_pk_mul_f32 v[4:5], v[4:5], v[36:37]
	v_pk_mul_f32 v[6:7], v[6:7], v[32:33]
	v_mov_b32_e32 v32, v51
	v_mov_b32_e32 v33, v53
	v_mul_f32_e32 v11, v11, v34
	v_pk_mul_f32 v[32:33], v[32:33], v[34:35]
	v_mov_b32_e32 v51, v52
	v_mul_f32_e32 v10, v12, v11
	v_cvt_pk_bf16_f32 v214, v0, v1
	v_cvt_pk_bf16_f32 v215, v2, v3
	v_cvt_pk_bf16_f32 v216, v4, v5
	v_cvt_pk_bf16_f32 v217, v6, v7
	v_pk_mul_f32 v[10:11], v[50:51], v[10:11]
	v_cvt_pk_bf16_f32 v227, v32, v33
	v_mfma_f32_32x32x16_bf16 v[48:63], v[28:31], v[214:217], v[64:79]
	v_cvt_pk_bf16_f32 v224, v8, v9
	v_cvt_pk_bf16_f32 v226, v10, v11
	v_mfma_f32_32x32x16_bf16 v[32:47], v[16:19], v[214:217], v[80:95]
	s_nop 0
	v_mfma_f32_32x32x16_bf16 v[48:63], v[24:27], v[224:227], v[48:63]
	v_mfma_f32_32x32x16_bf16 v[32:47], v[20:23], v[224:227], v[32:47]
	v_mfma_f32_32x32x16_bf16 v[16:31], v[168:171], v[214:217], v[96:111]
	v_mfma_f32_32x32x16_bf16 v[0:15], v[164:167], v[214:217], v[112:127]
	v_mfma_f32_32x32x16_bf16 v[16:31], v[172:175], v[224:227], v[16:31]
	v_mfma_f32_32x32x16_bf16 v[0:15], v[160:163], v[224:227], v[0:15]

; DEV f32x16 mfma32(bf16x8 a, bf16x8 b, f32x16 c) { return __builtin_amdgcn_mfma_f32_32x32x16_bf16(a, b, c, 0, 0, 0); }
; template <bool DIAG>
; DEV void sb_tile(const char* lk, const char* lv, const int ko0, const int vo0, const bf16x8 (&qf)[8], f32x16 (&O)[4], float& accp,
;                  const int l31, const int hh) {
;   f32x16 z;
;   for (int g = 0; g < 16; ++g) z[g] = 0.f;
;   {
;     bf16x8 kf[8];
; #pragma unroll
;     for (int s = 0; s < 8; ++s) kf[s] = *(const bf16x8*)(lk + (ko0 ^ (32 * s)));
;     __builtin_amdgcn_sched_barrier(0);
; #pragma unroll
;     for (int s = 0; s < 8; ++s) z = mfma32(kf[s], qf[s], z);
;   }
;   bf16x8 vf[4][2];
; #pragma unroll
;   for (int d = 0; d < 4; ++d) { vf[d][0] = *(const bf16x8*)(lv + d * 4096 + vo0); vf[d][1] = *(const bf16x8*)(lv + d * 4096 + (vo0 ^ 32)); }
;   __builtin_amdgcn_sched_barrier(0);
;   float be[16], om[16];
; #pragma unroll
;   for (int g = 0; g < 16; ++g) {
;     const float e = __builtin_amdgcn_exp2f(fminf(-z[g], 120.f));
;     be[g] = __builtin_amdgcn_rcpf(1.f + e);
;     om[g] = e * be[g];
;     if (DIAG) { const int kl = (g & 3) + 8 * (g >> 2) + 4 * hh; if (kl >= l31) { be[g] = 0.f; om[g] = 1.f; } }
;   }
;   float gp[4], pp[4], tot[4];
; #pragma unroll
;   for (int q = 0; q < 4; ++q) { gp[q] = (om[4 * q] * om[4 * q + 1]) * (om[4 * q + 2] * om[4 * q + 3]); pp[q] = __shfl_xor(gp[q], 32); tot[q] = gp[q] * pp[q]; }
; DEV void sb_block(const Params& p, int item) {
;     ...
;     if (2 * j == qt) sb_tile<true>(lb_, lb_, ko0, vo0, qf, O, accp, l31, hh);
.LBB0_570:
	s_nop 9
	ds_read_b128 v[0:3], v195
	ds_read_b128 v[16:19], v196
	ds_read_b128 v[20:23], v207
	ds_read_b128 v[24:27], v208
	ds_read_b128 v[28:31], v209
	ds_read_b128 v[32:35], v210
	ds_read_b128 v[36:39], v211
	ds_read_b128 v[48:51], v212
	s_waitcnt lgkmcnt(0)
	v_mfma_f32_32x32x16_bf16 v[0:15], v[0:3], v[128:131], 0
	v_mfma_f32_32x32x16_bf16 v[0:15], v[16:19], v[132:135], v[0:15]
	v_add_u32_e32 v16, s92, v193
	v_xad_u32 v17, v193, 32, s92
	v_mfma_f32_32x32x16_bf16 v[0:15], v[20:23], v[136:139], v[0:15]
	v_mfma_f32_32x32x16_bf16 v[0:15], v[24:27], v[140:143], v[0:15]
	v_mfma_f32_32x32x16_bf16 v[0:15], v[28:31], v[144:147], v[0:15]
	v_mfma_f32_32x32x16_bf16 v[0:15], v[32:35], v[148:151], v[0:15]
	v_mfma_f32_32x32x16_bf16 v[0:15], v[36:39], v[152:155], v[0:15]
	ds_read_b128 v[44:47], v16
	ds_read_b128 v[32:35], v16 offset:4096
	ds_read_b128 v[40:43], v17
	ds_read_b128 v[36:39], v17 offset:4096
	ds_read_b128 v[24:27], v16 offset:8192
	ds_read_b128 v[20:23], v16 offset:12288
	ds_read_b128 v[28:31], v17 offset:8192
	ds_read_b128 v[16:19], v17 offset:12288
	v_mfma_f32_32x32x16_bf16 v[0:15], v[48:51], v[156:159], v[0:15]
	s_nop 11
	v_min_f32_e64 v0, -v0, s32
	v_exp_f32_e32 v0, v0
	v_min_f32_e64 v1, -v1, s32
	v_exp_f32_e32 v1, v1
	v_add_f32_e32 v48, 1.0, v0
	v_rcp_f32_e32 v56, v48
	v_add_f32_e32 v48, 1.0, v1
	v_min_f32_e64 v2, -v2, s32
	v_rcp_f32_e32 v57, v48
	v_exp_f32_e32 v48, v2
	v_min_f32_e64 v2, -v3, s32
	v_exp_f32_e32 v3, v2
	v_add_f32_e32 v2, 1.0, v48
	v_rcp_f32_e32 v58, v2
	v_mul_f32_e32 v1, v1, v57
	v_add_f32_e32 v2, 1.0, v3
	v_rcp_f32_e32 v59, v2
	v_cndmask_b32_e64 v2, 1.0, v1, s[14:15]
	v_mul_f32_e32 v1, v48, v58
	v_cndmask_b32_e64 v48, 1.0, v1, s[16:17]
	v_mul_f32_e32 v1, v3, v59
	v_min_f32_e64 v3, -v4, s32
	v_exp_f32_e32 v3, v3
	v_min_f32_e64 v4, -v5, s32
	v_exp_f32_e32 v5, v4
	v_cndmask_b32_e64 v4, 1.0, v1, s[18:19]
	v_add_f32_e32 v1, 1.0, v3
	v_rcp_f32_e32 v60, v1
	v_add_f32_e32 v1, 1.0, v5
	v_rcp_f32_e32 v61, v1
	v_min_f32_e64 v1, -v6, s32
	v_exp_f32_e32 v1, v1
	v_mul_f32_e32 v3, v3, v60
	v_cndmask_b32_e64 v6, 1.0, v3, s[20:21]
	v_mul_f32_e32 v3, v5, v61
	v_add_f32_e32 v5, 1.0, v1
	v_rcp_f32_e32 v62, v5
	v_min_f32_e64 v5, -v7, s32
	v_exp_f32_e32 v5, v5
	v_mul_f32_e32 v1, v1, v62
	v_cndmask_b32_e64 v51, 1.0, v1, s[24:25]
	v_cndmask_b32_e64 v50, 1.0, v3, s[22:23]
	v_add_f32_e32 v1, 1.0, v5
	v_rcp_f32_e32 v63, v1
	v_min_f32_e64 v1, -v8, s32
	v_exp_f32_e32 v1, v1
	v_min_f32_e64 v3, -v9, s32
	v_exp_f32_e32 v3, v3
	v_mul_f32_e32 v5, v5, v63
	v_add_f32_e32 v7, 1.0, v1
	v_rcp_f32_e32 v160, v7
	v_add_f32_e32 v7, 1.0, v3
	v_rcp_f32_e32 v161, v7
	v_cndmask_b32_e64 v7, 1.0, v5, s[26:27]
	v_mul_f32_e32 v1, v1, v160
	v_cndmask_b32_e64 v8, 1.0, v1, s[28:29]
	v_mul_f32_e32 v1, v3, v161
	v_min_f32_e64 v3, -v10, s32
	v_exp_f32_e32 v3, v3
	v_min_f32_e64 v5, -v11, s32
	v_exp_f32_e32 v5, v5
	v_cndmask_b32_e64 v10, 1.0, v1, s[30:31]
	v_add_f32_e32 v1, 1.0, v3
	v_rcp_f32_e32 v162, v1
	v_add_f32_e32 v1, 1.0, v5
	v_rcp_f32_e32 v163, v1
	v_min_f32_e64 v1, -v12, s32
	v_exp_f32_e32 v1, v1
	v_mul_f32_e32 v3, v3, v162
	v_cndmask_b32_e64 v11, 1.0, v3, s[34:35]
	v_mul_f32_e32 v3, v5, v163
	v_add_f32_e32 v5, 1.0, v1
	v_rcp_f32_e32 v164, v5
	v_min_f32_e64 v5, -v13, s32
	v_exp_f32_e32 v5, v5
	v_mul_f32_e32 v1, v1, v164
	v_cndmask_b32_e64 v12, 1.0, v1, s[38:39]
	v_cndmask_b32_e64 v9, 1.0, v3, s[36:37]
	v_add_f32_e32 v1, 1.0, v5
	v_rcp_f32_e32 v165, v1
	v_min_f32_e64 v1, -v14, s32
	v_exp_f32_e32 v1, v1
	v_min_f32_e64 v3, -v15, s32
	v_exp_f32_e32 v3, v3
	v_mul_f32_e32 v5, v5, v165
	v_add_f32_e32 v13, 1.0, v1
	v_rcp_f32_e32 v166, v13
	v_add_f32_e32 v13, 1.0, v3
	v_rcp_f32_e32 v167, v13
	v_cndmask_b32_e64 v14, 1.0, v5, s[40:41]
	v_mul_f32_e32 v1, v1, v166
	v_cndmask_b32_e64 v15, 1.0, v1, s[42:43]
	v_mul_f32_e32 v1, v3, v167
	v_and_b32_e32 v3, 64, v219
	v_cndmask_b32_e64 v13, 1.0, v1, s[44:45]
	v_xor_b32_e32 v1, 32, v219
	v_add_u32_e32 v3, 64, v3
	v_cmp_lt_i32_e32 vcc, v1, v3
	v_pk_mul_f32 v[52:53], v[10:11], v[8:9]
	v_mul_f32_e32 v0, v0, v56
	v_cndmask_b32_e32 v1, v219, v1, vcc
	v_lshlrev_b32_e32 v168, 2, v1
	v_mul_f32_e32 v1, v52, v53
	v_pk_mul_f32 v[52:53], v[14:15], v[12:13]
	v_mov_b32_e32 v8, v1
	s_nop 1
	v_permlane32_swap_b32_e32 v1, v8
	v_mul_f32_e32 v5, v52, v53
	v_mov_b32_e32 v12, v5
	s_nop 1
	v_permlane32_swap_b32_e32 v5, v12
	v_pk_mul_f32 v[52:53], v[50:51], v[6:7]
	v_cndmask_b32_e64 v0, 1.0, v0, s[12:13]
	v_pk_mul_f32 v[52:53], v[52:53], v[52:53] op_sel:[0,1] op_sel_hi:[1,0]
	v_mov_b32_e32 v3, v52
	s_nop 1
	v_permlane32_swap_b32_e32 v52, v3
	s_waitcnt lgkmcnt(0)
; DEV f32x16 mfma32(bf16x8 a, bf16x8 b, f32x16 c) { return __builtin_amdgcn_mfma_f32_32x32x16_bf16(a, b, c, 0, 0, 0); }
; template <bool DIAG>
; DEV void sb_tile(const char* lk, const char* lv, const int ko0, const int vo0, const bf16x8 (&qf)[8], f32x16 (&O)[4], float& accp,
;                  const int l31, const int hh) {
;     ...
;   for (int q = 0; q < 4; ++q) { gp[q] = (om[4 * q] * om[4 * q + 1]) * (om[4 * q + 2] * om[4 * q + 3]); pp[q] = __shfl_xor(gp[q], 32); tot[q] = gp[q] * pp[q]; }
;   float suf[4];
;   suf[3] = accp; suf[2] = suf[3] * tot[3]; suf[1] = suf[2] * tot[2]; suf[0] = suf[1] * tot[1];
;   accp = suf[0] * tot[0];
;   f32x16 w;
; #pragma unroll
;   for (int q = 0; q < 4; ++q) {
;     float a = suf[q] * (hh == 0 ? pp[q] : 1.f);
;     w[4 * q + 3] = be[4 * q + 3] * a; a *= om[4 * q + 3];
;     w[4 * q + 2] = be[4 * q + 2] * a; a *= om[4 * q + 2];
;     w[4 * q + 1] = be[4 * q + 1] * a; a *= om[4 * q + 1];
;     w[4 * q + 0] = be[4 * q + 0] * a;
;   }
;   const bf16x8 w0 = cvt8<0>(w), w1 = cvt8<1>(w);
; #pragma unroll
;   for (int d = 0; d < 4; ++d) { O[d] = mfma32(vf[d][0], w0, O[d]); O[d] = mfma32(vf[d][1], w1, O[d]); }
	v_mul_f32_e32 v49, v1, v8
	v_mul_f32_e32 v1, v5, v12
	v_mul_f32_e32 v5, v199, v1
	v_mov_b32_e32 v1, v52
	v_pk_mul_f32 v[0:1], v[0:1], v[2:3]
	v_pk_mul_f32 v[52:53], v[48:49], v[4:5]
	v_cndmask_b32_e64 v49, 1.0, v3, s[10:11]
	v_pk_mul_f32 v[54:55], v[0:1], v[52:53]
	v_mov_b32_e32 v52, v54
	s_nop 1
	v_permlane32_swap_b32_e32 v54, v52
	v_cndmask_b32_e64 v3, 1.0, v8, s[10:11]
	v_cndmask_b32_e64 v1, 0, v57, s[14:15]
	v_cndmask_b32_e64 v57, 0, v59, s[18:19]
	v_cndmask_b32_e64 v59, 0, v61, s[22:23]
	s_waitcnt lgkmcnt(0)
	v_cndmask_b32_e64 v6, 1.0, v52, s[10:11]
	v_cndmask_b32_e64 v61, 0, v63, s[26:27]
	v_cndmask_b32_e64 v63, 0, v161, s[30:31]
	v_cndmask_b32_e64 v161, 0, v163, s[36:37]
	v_cndmask_b32_e64 v163, 0, v165, s[40:41]
	v_cndmask_b32_e64 v165, 0, v167, s[44:45]
	v_mul_f32_e32 v167, v3, v5
	v_mul_f32_e32 v5, v6, v55
	v_mul_f32_e32 v4, v4, v5
	v_mul_f32_e32 v3, v48, v4
	v_cndmask_b32_e64 v0, 0, v56, s[12:13]
	v_cndmask_b32_e64 v56, 0, v58, s[16:17]
	v_mul_f32_e32 v2, v2, v3
	v_pk_mul_f32 v[0:1], v[0:1], v[2:3]
	v_pk_mul_f32 v[2:3], v[56:57], v[4:5]
	v_mul_f32_e32 v5, v49, v53
	v_mul_f32_e32 v4, v7, v5
	v_mul_f32_e32 v7, v51, v4
	v_cndmask_b32_e64 v58, 0, v60, s[20:21]
	v_cndmask_b32_e64 v60, 0, v62, s[24:25]
	v_mul_f32_e32 v6, v50, v7
	v_pk_mul_f32 v[6:7], v[58:59], v[6:7]
	v_pk_mul_f32 v[4:5], v[60:61], v[4:5]
	v_cvt_pk_bf16_f32 v0, v0, v1
	v_cvt_pk_bf16_f32 v1, v2, v3
	v_cvt_pk_bf16_f32 v2, v6, v7
	v_cvt_pk_bf16_f32 v3, v4, v5
	v_cndmask_b32_e64 v12, 1.0, v12, s[10:11]
	v_mul_f32_e32 v49, v199, v12
	v_mfma_f32_32x32x16_bf16 v[64:79], v[44:47], v[0:3], v[64:79]
	v_cndmask_b32_e64 v62, 0, v160, s[28:29]
	v_cndmask_b32_e64 v160, 0, v162, s[34:35]
	v_cndmask_b32_e64 v162, 0, v164, s[38:39]
	v_cndmask_b32_e64 v164, 0, v166, s[42:43]
	v_mul_f32_e32 v166, v9, v167
	v_mul_f32_e32 v48, v49, v13
	v_mul_f32_e32 v11, v11, v166
	v_mfma_f32_32x32x16_bf16 v[80:95], v[32:35], v[0:3], v[80:95]
	v_mul_f32_e32 v5, v15, v48
	v_mul_f32_e32 v10, v10, v11
	v_mul_f32_e32 v4, v14, v5
	v_mul_f32_e64 v8, v160, v166
	v_mul_f32_e64 v9, v161, v167
	v_pk_mul_f32 v[10:11], v[62:63], v[10:11]
	v_pk_mul_f32 v[12:13], v[164:165], v[48:49]
	v_pk_mul_f32 v[6:7], v[162:163], v[4:5]
	v_mfma_f32_32x32x16_bf16 v[96:111], v[24:27], v[0:3], v[96:111]
	v_cvt_pk_bf16_f32 v4, v10, v11
	v_cvt_pk_bf16_f32 v5, v8, v9
	v_cvt_pk_bf16_f32 v6, v6, v7
	v_cvt_pk_bf16_f32 v7, v12, v13
	v_mfma_f32_32x32x16_bf16 v[112:127], v[20:23], v[0:3], v[112:127]
	v_mul_f32_e32 v0, v54, v52
	v_mul_f32_e32 v197, v0, v55
	v_mfma_f32_32x32x16_bf16 v[64:79], v[40:43], v[4:7], v[64:79]
	v_mfma_f32_32x32x16_bf16 v[80:95], v[36:39], v[4:7], v[80:95]
	s_nop 10
	v_mov_b64_e32 v[48:49], v[64:65]
	v_mov_b64_e32 v[50:51], v[66:67]
	v_mov_b64_e32 v[52:53], v[68:69]
	v_mov_b64_e32 v[54:55], v[70:71]
	v_mov_b64_e32 v[56:57], v[72:73]
	v_mov_b64_e32 v[58:59], v[74:75]
	v_mov_b64_e32 v[60:61], v[76:77]
	v_mfma_f32_32x32x16_bf16 v[96:111], v[28:31], v[4:7], v[96:111]
	v_mov_b64_e32 v[32:33], v[80:81]
	v_mov_b64_e32 v[34:35], v[82:83]
	v_mov_b64_e32 v[36:37], v[84:85]
	v_mov_b64_e32 v[38:39], v[86:87]
	v_mov_b64_e32 v[40:41], v[88:89]
	v_mov_b64_e32 v[42:43], v[90:91]
	v_mov_b64_e32 v[44:45], v[92:93]
	v_mfma_f32_32x32x16_bf16 v[112:127], v[16:19], v[4:7], v[112:127]
	s_nop 3
	v_mov_b64_e32 v[16:17], v[96:97]
	v_mov_b64_e32 v[18:19], v[98:99]
	v_mov_b64_e32 v[20:21], v[100:101]
	v_mov_b64_e32 v[22:23], v[102:103]
	v_mov_b64_e32 v[24:25], v[104:105]
	v_mov_b64_e32 v[26:27], v[106:107]
	v_mov_b64_e32 v[28:29], v[108:109]
	s_nop 0
	v_mov_b64_e32 v[0:1], v[112:113]
	v_mov_b64_e32 v[2:3], v[114:115]
	v_mov_b64_e32 v[4:5], v[116:117]
	v_mov_b64_e32 v[6:7], v[118:119]
	v_mov_b64_e32 v[8:9], v[120:121]
	v_mov_b64_e32 v[10:11], v[122:123]
	v_mov_b64_e32 v[12:13], v[124:125]
	v_mov_b64_e32 v[14:15], v[126:127]
	v_mov_b64_e32 v[30:31], v[110:111]
	v_mov_b64_e32 v[46:47], v[94:95]
	v_mov_b64_e32 v[62:63], v[78:79]
	s_branch .LBB0_542

; DEV f32x16 mfma32(bf16x8 a, bf16x8 b, f32x16 c) { return __builtin_amdgcn_mfma_f32_32x32x16_bf16(a, b, c, 0, 0, 0); }
; template <bool DIAG>
; DEV void sb_tile(const char* lk, const char* lv, const int ko0, const int vo0, const bf16x8 (&qf)[8], f32x16 (&O)[4], float& accp,
;                  const int l31, const int hh) {
;   f32x16 z;
;   for (int g = 0; g < 16; ++g) z[g] = 0.f;
;   {
;     bf16x8 kf[8];
; #pragma unroll
;     for (int s = 0; s < 8; ++s) kf[s] = *(const bf16x8*)(lk + (ko0 ^ (32 * s)));
;     __builtin_amdgcn_sched_barrier(0);
; #pragma unroll
;     for (int s = 0; s < 8; ++s) z = mfma32(kf[s], qf[s], z);
;   }
;   bf16x8 vf[4][2];
; #pragma unroll
;   for (int d = 0; d < 4; ++d) { vf[d][0] = *(const bf16x8*)(lv + d * 4096 + vo0); vf[d][1] = *(const bf16x8*)(lv + d * 4096 + (vo0 ^ 32)); }
;   __builtin_amdgcn_sched_barrier(0);
;   float be[16], om[16];
; #pragma unroll
;   for (int g = 0; g < 16; ++g) {
;     const float e = __builtin_amdgcn_exp2f(fminf(-z[g], 120.f));
;     be[g] = __builtin_amdgcn_rcpf(1.f + e);
;     om[g] = e * be[g];
;     if (DIAG) { const int kl = (g & 3) + 8 * (g >> 2) + 4 * hh; if (kl >= l31) { be[g] = 0.f; om[g] = 1.f; } }
;   }
;   float gp[4], pp[4], tot[4];
; #pragma unroll
;   for (int q = 0; q < 4; ++q) { gp[q] = (om[4 * q] * om[4 * q + 1]) * (om[4 * q + 2] * om[4 * q + 3]); pp[q] = __shfl_xor(gp[q], 32); tot[q] = gp[q] * pp[q]; }
; DEV void sb_block(const Params& p, int item) {
;     ...
;     else if (2 * j + 1 < qt) sb_tile<false>(lb_ + 32 * 256, lb_, ko0, vo0 ^ 64, qf, O, accp, l31, hh);
.LBB0_1211:
	s_and_b32 s66, s33, 0x18000
	s_add_i32 s92, s66, 0
	s_add_i32 s90, s74, s69
	v_mov_b32_e32 v168, v205
	v_mov_b32_e32 v193, v206
	s_cmp_lg_u32 s89, s69
	s_mov_b64 s[66:67], -1
	s_cbranch_scc0 .LBB0_1215
	s_add_i32 s66, s90, 7
	s_cmp_ge_i32 s66, s76
	s_cbranch_scc1 .Lsb_skip_A1
	v_add_u32_e32 v64, s92, v168
	v_xad_u32 v68, v168, 32, s92
	ds_read_b128 v[64:67], v64 offset:8192
	ds_read_b128 v[80:83], v68 offset:8192
	v_xad_u32 v68, v168, 64, s92
	v_xor_b32_e32 v69, 0x60, v168
	v_add_u32_e32 v69, s92, v69
	ds_read_b128 v[84:87], v68 offset:8192
	ds_read_b128 v[88:91], v69 offset:8192
	v_xor_b32_e32 v68, 0x80, v168
	v_add_u32_e32 v68, s92, v68
	v_xor_b32_e32 v69, 0xa0, v168
	v_add_u32_e32 v69, s92, v69
	ds_read_b128 v[92:95], v68 offset:8192
	ds_read_b128 v[96:99], v69 offset:8192
	v_xor_b32_e32 v68, 0xc0, v168
	v_add_u32_e32 v68, s92, v68
	v_xor_b32_e32 v69, 0xe0, v168
	v_add_u32_e32 v69, s92, v69
	ds_read_b128 v[100:103], v68 offset:8192
	ds_read_b128 v[104:107], v69 offset:8192
	s_waitcnt lgkmcnt(0)
	v_mfma_f32_32x32x16_bf16 v[64:79], v[64:67], v[128:131], 0
	v_mfma_f32_32x32x16_bf16 v[64:79], v[80:83], v[132:135], v[64:79]
	v_xor_b32_e32 v80, 0x60, v193
	v_mfma_f32_32x32x16_bf16 v[64:79], v[84:87], v[136:139], v[64:79]
	v_mfma_f32_32x32x16_bf16 v[64:79], v[88:91], v[140:143], v[64:79]
	v_xad_u32 v88, v193, 64, s92
	v_add_u32_e32 v89, s92, v80
	v_mfma_f32_32x32x16_bf16 v[64:79], v[92:95], v[144:147], v[64:79]
	v_mfma_f32_32x32x16_bf16 v[64:79], v[96:99], v[148:151], v[64:79]
	v_mfma_f32_32x32x16_bf16 v[64:79], v[100:103], v[152:155], v[64:79]
	ds_read_b128 v[84:87], v88
	ds_read_b128 v[96:99], v88 offset:4096
	ds_read_b128 v[80:83], v89
	ds_read_b128 v[100:103], v89 offset:4096
	ds_read_b128 v[112:115], v88 offset:8192
	ds_read_b128 v[164:167], v88 offset:12288
	ds_read_b128 v[116:119], v89 offset:8192
	ds_read_b128 v[160:163], v89 offset:12288
	v_mfma_f32_32x32x16_bf16 v[64:79], v[104:107], v[156:159], v[64:79]
	s_nop 11
	v_min_f32_e64 v68, -v68, s32
	v_exp_f32_e32 v90, v68
	v_min_f32_e64 v68, -v69, s32
	v_exp_f32_e32 v91, v68
	v_add_f32_e32 v68, 1.0, v90
	v_min_f32_e64 v73, -v73, s32
	v_add_f32_e32 v69, 1.0, v91
	v_rcp_f32_e32 v68, v68
	v_rcp_f32_e32 v69, v69
	v_exp_f32_e32 v104, v73
	v_max_f32_e64 v73, -v74, -v74
	v_max_f32_e64 v74, -v75, -v75
	v_min_f32_e64 v72, -v72, s32
	v_min_f32_e32 v74, 0x42f00000, v74
	v_min_f32_e64 v75, -v77, s32
	v_max_f32_e64 v77, -v79, -v79
	v_and_b32_e32 v79, 64, v219
	v_exp_f32_e32 v72, v72
	v_exp_f32_e32 v105, v74
	v_max_f32_e64 v74, -v76, -v76
	v_exp_f32_e32 v76, v75
	v_max_f32_e64 v75, -v78, -v78
	v_xor_b32_e32 v78, 32, v219
	v_add_u32_e32 v79, 64, v79
	v_min_f32_e32 v73, 0x42f00000, v73
	v_cmp_lt_i32_e32 vcc, v78, v79
	v_pk_mul_f32 v[90:91], v[90:91], v[68:69]
	v_exp_f32_e32 v73, v73
	v_cndmask_b32_e32 v78, v219, v78, vcc
	v_lshlrev_b32_e32 v170, 2, v78
	v_pk_mul_f32 v[78:79], v[90:91], v[90:91] op_sel_hi:[0,1]
	v_add_f32_e32 v78, 1.0, v72
	v_rcp_f32_e32 v108, v78
	v_add_f32_e32 v78, 1.0, v104
	v_rcp_f32_e32 v110, v78
	v_add_f32_e32 v78, 1.0, v73
	v_rcp_f32_e32 v109, v78
	v_add_f32_e32 v78, 1.0, v105
	v_min_f32_e32 v74, 0x42f00000, v74
	v_rcp_f32_e32 v111, v78
	v_exp_f32_e32 v74, v74
	v_min_f32_e32 v75, 0x42f00000, v75
	v_exp_f32_e32 v75, v75
	v_min_f32_e32 v77, 0x42f00000, v77
	v_exp_f32_e32 v77, v77
	v_pk_mul_f32 v[72:73], v[72:73], v[108:109]
	v_pk_mul_f32 v[104:105], v[104:105], v[110:111]
	v_pk_mul_f32 v[120:121], v[72:73], v[104:105]
	v_add_f32_e32 v72, 1.0, v74
	v_rcp_f32_e32 v122, v72
	v_add_f32_e32 v72, 1.0, v76
	v_rcp_f32_e32 v124, v72
	v_add_f32_e32 v72, 1.0, v75
	v_min_f32_e64 v70, -v70, s32
	v_rcp_f32_e32 v123, v72
	v_add_f32_e32 v72, 1.0, v77
	v_exp_f32_e32 v92, v70
	v_rcp_f32_e32 v125, v72
	v_min_f32_e64 v70, -v71, s32
	v_min_f32_e64 v67, -v67, s32
	v_exp_f32_e32 v93, v70
	v_min_f32_e64 v64, -v64, s32
	v_exp_f32_e32 v196, v67
	v_exp_f32_e32 v88, v64
	v_pk_mul_f32 v[74:75], v[74:75], v[122:123]
	v_pk_mul_f32 v[76:77], v[76:77], v[124:125]
	v_add_f32_e32 v70, 1.0, v92
	v_pk_mul_f32 v[126:127], v[74:75], v[76:77]
	v_add_f32_e32 v71, 1.0, v93
	v_mul_f32_e32 v72, v126, v127
	v_add_f32_e32 v67, 1.0, v196
	v_rcp_f32_e32 v70, v70
	v_rcp_f32_e32 v71, v71
	v_pk_mul_f32 v[120:121], v[120:121], v[120:121] op_sel:[0,1] op_sel_hi:[1,0]
	v_mov_b32_e32 v74, v72
	s_nop 1
	v_permlane32_swap_b32_e32 v72, v74
	v_add_f32_e32 v64, 1.0, v88
	v_min_f32_e64 v66, -v66, s32
	v_rcp_f32_e32 v67, v67
	v_mov_b32_e32 v121, v120
	s_nop 1
	v_permlane32_swap_b32_e32 v120, v121
	v_rcp_f32_e32 v64, v64
	v_min_f32_e64 v65, -v65, s32
	v_exp_f32_e32 v94, v66
	v_exp_f32_e32 v169, v65
	v_pk_mul_f32 v[92:93], v[92:93], v[70:71]
	s_waitcnt lgkmcnt(0)
; DEV f32x16 mfma32(bf16x8 a, bf16x8 b, f32x16 c) { return __builtin_amdgcn_mfma_f32_32x32x16_bf16(a, b, c, 0, 0, 0); }
; template <bool DIAG>
; DEV void sb_tile(const char* lk, const char* lv, const int ko0, const int vo0, const bf16x8 (&qf)[8], f32x16 (&O)[4], float& accp,
;                  const int l31, const int hh) {
;     ...
;   for (int q = 0; q < 4; ++q) { gp[q] = (om[4 * q] * om[4 * q + 1]) * (om[4 * q + 2] * om[4 * q + 3]); pp[q] = __shfl_xor(gp[q], 32); tot[q] = gp[q] * pp[q]; }
;   float suf[4];
;   suf[3] = accp; suf[2] = suf[3] * tot[3]; suf[1] = suf[2] * tot[2]; suf[0] = suf[1] * tot[1];
;   accp = suf[0] * tot[0];
;   f32x16 w;
; #pragma unroll
;   for (int q = 0; q < 4; ++q) {
;     float a = suf[q] * (hh == 0 ? pp[q] : 1.f);
;     w[4 * q + 3] = be[4 * q + 3] * a; a *= om[4 * q + 3];
;     w[4 * q + 2] = be[4 * q + 2] * a; a *= om[4 * q + 2];
;     w[4 * q + 1] = be[4 * q + 1] * a; a *= om[4 * q + 1];
;     w[4 * q + 0] = be[4 * q + 0] * a;
;   }
;   const bf16x8 w0 = cvt8<0>(w), w1 = cvt8<1>(w);
; #pragma unroll
;   for (int d = 0; d < 4; ++d) { O[d] = mfma32(vf[d][0], w0, O[d]); O[d] = mfma32(vf[d][1], w1, O[d]); }
	v_mul_f32_e32 v127, v72, v74
	v_pk_mul_f32 v[106:107], v[92:93], v[92:93] op_sel_hi:[0,1]
	v_mov_b32_e32 v126, v67
	v_add_f32_e32 v66, 1.0, v94
	v_mov_b32_e32 v89, v79
	v_cndmask_b32_e64 v72, 1.0, v121, s[10:11]
	v_mov_b32_e32 v78, v109
	v_mov_b32_e32 v79, v111
	v_mov_b32_e32 v109, v110
	v_pk_mul_f32 v[110:111], v[196:197], v[126:127]
	v_mov_b32_e32 v106, v64
	v_add_f32_e32 v65, 1.0, v169
	v_rcp_f32_e32 v66, v66
	v_mul_f32_e32 v127, v72, v111
	v_pk_mul_f32 v[88:89], v[88:89], v[106:107]
	v_rcp_f32_e32 v65, v65
	v_mul_f32_e32 v126, v105, v127
	v_mov_b32_e32 v105, v89
	s_nop 1
	v_permlane32_swap_b32_e32 v89, v105
	v_mov_b32_e32 v95, v120
	v_mov_b32_e32 v120, v66
	v_mul_f32_e32 v73, v73, v126
	v_pk_mul_f32 v[94:95], v[94:95], v[120:121]
	v_mul_f32_e32 v72, v104, v73
	v_mul_f32_e32 v104, v169, v65
	v_pk_mul_f32 v[120:121], v[94:95], v[110:111]
	s_waitcnt lgkmcnt(0)
	v_pk_mul_f32 v[88:89], v[88:89], v[104:105]
	v_cndmask_b32_e64 v90, 1.0, v105, s[10:11]
	v_pk_mul_f32 v[88:89], v[88:89], v[120:121]
	v_mov_b32_e32 v95, v88
	s_nop 1
	v_permlane32_swap_b32_e32 v88, v95
	v_cndmask_b32_e64 v74, 1.0, v74, s[10:11]
	v_pk_mul_f32 v[78:79], v[78:79], v[126:127]
	v_pk_mul_f32 v[72:73], v[108:109], v[72:73]
	v_cvt_pk_bf16_f32 v209, v78, v79
	s_waitcnt lgkmcnt(0)
	v_mul_f32_e32 v88, v88, v95
	v_mul_f32_e32 v199, v88, v89
	v_cndmask_b32_e64 v88, 1.0, v95, s[10:11]
	v_mul_f32_e32 v89, v88, v89
	v_mul_f32_e32 v88, v110, v89
	v_pk_mul_f32 v[66:67], v[66:67], v[88:89]
	v_mul_f32_e32 v89, v90, v121
	v_mul_f32_e32 v95, v94, v88
	v_mul_f32_e32 v88, v93, v89
	v_mul_f32_e32 v93, v92, v88
	v_mul_f32_e32 v92, v91, v93
	v_mul_f32_e32 v91, v197, v74
	v_mul_f32_e32 v90, v77, v91
	v_mul_f32_e32 v94, v104, v95
	v_mul_f32_e32 v75, v75, v90
	v_pk_mul_f32 v[64:65], v[64:65], v[94:95]
	v_pk_mul_f32 v[68:69], v[68:69], v[92:93]
	v_pk_mul_f32 v[70:71], v[70:71], v[88:89]
	v_mov_b32_e32 v88, v123
	v_mov_b32_e32 v123, v124
	v_mul_f32_e32 v74, v76, v75
	v_pk_mul_f32 v[74:75], v[122:123], v[74:75]
	v_cvt_pk_bf16_f32 v170, v64, v65
	v_cvt_pk_bf16_f32 v171, v66, v67
	v_cvt_pk_bf16_f32 v172, v68, v69
	v_cvt_pk_bf16_f32 v173, v70, v71
	v_cvt_pk_bf16_f32 v208, v72, v73
	v_cvt_pk_bf16_f32 v210, v74, v75
	v_mfma_f32_32x32x16_bf16 v[64:79], v[84:87], v[170:173], v[48:63]
	v_mov_b32_e32 v89, v125
	v_mul_f32_e64 v88, v88, v90
	v_mul_f32_e64 v89, v89, v91
	v_cvt_pk_bf16_f32 v211, v88, v89
	s_nop 1
	v_mfma_f32_32x32x16_bf16 v[64:79], v[80:83], v[208:211], v[64:79]
	v_mfma_f32_32x32x16_bf16 v[80:95], v[96:99], v[170:173], v[32:47]
	v_mfma_f32_32x32x16_bf16 v[80:95], v[100:103], v[208:211], v[80:95]
	v_mfma_f32_32x32x16_bf16 v[96:111], v[112:115], v[170:173], v[16:31]
	v_mfma_f32_32x32x16_bf16 v[96:111], v[116:119], v[208:211], v[96:111]
	v_mfma_f32_32x32x16_bf16 v[112:127], v[164:167], v[170:173], v[0:15]
	v_mfma_f32_32x32x16_bf16 v[112:127], v[160:163], v[208:211], v[112:127]

; DEV f32x16 mfma32(bf16x8 a, bf16x8 b, f32x16 c) { return __builtin_amdgcn_mfma_f32_32x32x16_bf16(a, b, c, 0, 0, 0); }
; template <bool DIAG>
; DEV void sb_tile(const char* lk, const char* lv, const int ko0, const int vo0, const bf16x8 (&qf)[8], f32x16 (&O)[4], float& accp,
;                  const int l31, const int hh) {
;   f32x16 z;
;   for (int g = 0; g < 16; ++g) z[g] = 0.f;
;   {
;     bf16x8 kf[8];
; #pragma unroll
;     for (int s = 0; s < 8; ++s) kf[s] = *(const bf16x8*)(lk + (ko0 ^ (32 * s)));
;     __builtin_amdgcn_sched_barrier(0);
; #pragma unroll
;     for (int s = 0; s < 8; ++s) z = mfma32(kf[s], qf[s], z);
;   }
;   bf16x8 vf[4][2];
; #pragma unroll
;   for (int d = 0; d < 4; ++d) { vf[d][0] = *(const bf16x8*)(lv + d * 4096 + vo0); vf[d][1] = *(const bf16x8*)(lv + d * 4096 + (vo0 ^ 32)); }
;   __builtin_amdgcn_sched_barrier(0);
;   float be[16], om[16];
; #pragma unroll
;   for (int g = 0; g < 16; ++g) {
;     const float e = __builtin_amdgcn_exp2f(fminf(-z[g], 120.f));
;     be[g] = __builtin_amdgcn_rcpf(1.f + e);
;     om[g] = e * be[g];
;     if (DIAG) { const int kl = (g & 3) + 8 * (g >> 2) + 4 * hh; if (kl >= l31) { be[g] = 0.f; om[g] = 1.f; } }
;   }
;   float gp[4], pp[4], tot[4];
; #pragma unroll
;   for (int q = 0; q < 4; ++q) { gp[q] = (om[4 * q] * om[4 * q + 1]) * (om[4 * q + 2] * om[4 * q + 3]); pp[q] = __shfl_xor(gp[q], 32); tot[q] = gp[q] * pp[q]; }
;   float suf[4];
;   suf[3] = accp; suf[2] = suf[3] * tot[3]; suf[1] = suf[2] * tot[2]; suf[0] = suf[1] * tot[1];
;   accp = suf[0] * tot[0];
;   f32x16 w;
; #pragma unroll
;   for (int q = 0; q < 4; ++q) {
;     float a = suf[q] * (hh == 0 ? pp[q] : 1.f);
;     w[4 * q + 3] = be[4 * q + 3] * a; a *= om[4 * q + 3];
;     w[4 * q + 2] = be[4 * q + 2] * a; a *= om[4 * q + 2];
;     w[4 * q + 1] = be[4 * q + 1] * a; a *= om[4 * q + 1];
;     w[4 * q + 0] = be[4 * q + 0] * a;
;   }
;   const bf16x8 w0 = cvt8<0>(w), w1 = cvt8<1>(w);
; #pragma unroll
;   for (int d = 0; d < 4; ++d) { O[d] = mfma32(vf[d][0], w0, O[d]); O[d] = mfma32(vf[d][1], w1, O[d]); }
; DEV void sb_block(const Params& p, int item) {
;     ...
;     else if (2 * j < qt) sb_tile<false>(lb_, lb_, ko0, vo0, qf, O, accp, l31, hh);
.LBB0_1217:
	s_cmp_lg_u32 s88, s69
	s_mov_b64 s[66:67], -1
	s_cbranch_scc0 .LBB0_1221
	s_add_i32 s90, s90, 6
	s_cmp_ge_i32 s90, s76
	s_cbranch_scc1 .Lsb_skip_B1
	ds_read_b128 v[0:3], v195
	ds_read_b128 v[16:19], v196
	ds_read_b128 v[20:23], v207
	ds_read_b128 v[24:27], v208
	ds_read_b128 v[28:31], v209
	ds_read_b128 v[32:35], v210
	ds_read_b128 v[36:39], v211
	ds_read_b128 v[40:43], v212
	s_waitcnt lgkmcnt(0)
	v_mfma_f32_32x32x16_bf16 v[0:15], v[0:3], v[128:131], 0
	v_mfma_f32_32x32x16_bf16 v[0:15], v[16:19], v[132:135], v[0:15]
	v_mfma_f32_32x32x16_bf16 v[0:15], v[20:23], v[136:139], v[0:15]
	v_mfma_f32_32x32x16_bf16 v[0:15], v[24:27], v[140:143], v[0:15]
	v_mfma_f32_32x32x16_bf16 v[0:15], v[28:31], v[144:147], v[0:15]
	v_mfma_f32_32x32x16_bf16 v[0:15], v[32:35], v[148:151], v[0:15]
	v_add_u32_e32 v32, s92, v193
	v_xad_u32 v33, v193, 32, s92
	ds_read_b128 v[28:31], v32
	ds_read_b128 v[16:19], v32 offset:4096
	ds_read_b128 v[24:27], v33
	ds_read_b128 v[20:23], v33 offset:4096
	ds_read_b128 v[168:171], v32 offset:8192
	ds_read_b128 v[164:167], v32 offset:12288
	ds_read_b128 v[172:175], v33 offset:8192
	ds_read_b128 v[160:163], v33 offset:12288
	v_mfma_f32_32x32x16_bf16 v[0:15], v[36:39], v[152:155], v[0:15]
	v_mfma_f32_32x32x16_bf16 v[0:15], v[40:43], v[156:159], v[0:15]
	s_nop 11
	v_min_f32_e64 v4, -v4, s32
	v_exp_f32_e32 v34, v4
	v_min_f32_e64 v4, -v5, s32
	v_exp_f32_e32 v35, v4
	v_add_f32_e32 v4, 1.0, v34
	v_min_f32_e64 v9, -v9, s32
	v_add_f32_e32 v5, 1.0, v35
	v_rcp_f32_e32 v4, v4
	v_rcp_f32_e32 v5, v5
	v_exp_f32_e32 v40, v9
	v_max_f32_e64 v9, -v10, -v10
	v_max_f32_e64 v10, -v11, -v11
	v_min_f32_e64 v8, -v8, s32
	v_min_f32_e32 v10, 0x42f00000, v10
	v_min_f32_e64 v11, -v13, s32
	v_max_f32_e64 v13, -v15, -v15
	v_and_b32_e32 v15, 64, v219
	v_exp_f32_e32 v8, v8
	v_exp_f32_e32 v41, v10
	v_max_f32_e64 v10, -v12, -v12
	v_exp_f32_e32 v12, v11
	v_max_f32_e64 v11, -v14, -v14
	v_xor_b32_e32 v14, 32, v219
	v_add_u32_e32 v15, 64, v15
	v_min_f32_e32 v9, 0x42f00000, v9
	v_cmp_lt_i32_e32 vcc, v14, v15
	v_pk_mul_f32 v[34:35], v[34:35], v[4:5]
	v_exp_f32_e32 v9, v9
	v_cndmask_b32_e32 v14, v219, v14, vcc
	v_lshlrev_b32_e32 v57, 2, v14
	v_pk_mul_f32 v[14:15], v[34:35], v[34:35] op_sel_hi:[0,1]
	v_add_f32_e32 v14, 1.0, v8
	v_rcp_f32_e32 v44, v14
	v_add_f32_e32 v14, 1.0, v40
	v_rcp_f32_e32 v46, v14
	v_add_f32_e32 v14, 1.0, v9
	v_rcp_f32_e32 v45, v14
	v_add_f32_e32 v14, 1.0, v41
	v_min_f32_e32 v10, 0x42f00000, v10
	v_rcp_f32_e32 v47, v14
	v_exp_f32_e32 v10, v10
	v_min_f32_e32 v11, 0x42f00000, v11
	v_exp_f32_e32 v11, v11
	v_min_f32_e32 v13, 0x42f00000, v13
	v_exp_f32_e32 v13, v13
	v_pk_mul_f32 v[8:9], v[8:9], v[44:45]
	v_pk_mul_f32 v[40:41], v[40:41], v[46:47]
	v_pk_mul_f32 v[48:49], v[8:9], v[40:41]
	v_add_f32_e32 v8, 1.0, v10
	v_rcp_f32_e32 v50, v8
	v_add_f32_e32 v8, 1.0, v12
	v_rcp_f32_e32 v52, v8
	v_add_f32_e32 v8, 1.0, v11
	v_min_f32_e64 v6, -v6, s32
	v_rcp_f32_e32 v51, v8
	v_add_f32_e32 v8, 1.0, v13
	v_exp_f32_e32 v36, v6
	v_rcp_f32_e32 v53, v8
	v_min_f32_e64 v6, -v7, s32
	v_min_f32_e64 v3, -v3, s32
	v_exp_f32_e32 v37, v6
	v_min_f32_e64 v0, -v0, s32
	v_exp_f32_e32 v198, v3
	v_exp_f32_e32 v32, v0
	v_pk_mul_f32 v[10:11], v[10:11], v[50:51]
	v_pk_mul_f32 v[12:13], v[12:13], v[52:53]
	v_add_f32_e32 v6, 1.0, v36
	v_pk_mul_f32 v[54:55], v[10:11], v[12:13]
	v_add_f32_e32 v7, 1.0, v37
	v_mul_f32_e32 v8, v54, v55
	v_add_f32_e32 v3, 1.0, v198
	v_rcp_f32_e32 v6, v6
	v_rcp_f32_e32 v7, v7
	v_pk_mul_f32 v[48:49], v[48:49], v[48:49] op_sel:[0,1] op_sel_hi:[1,0]
	v_mov_b32_e32 v10, v8
	s_nop 1
	v_permlane32_swap_b32_e32 v8, v10
	v_add_f32_e32 v0, 1.0, v32
	v_min_f32_e64 v2, -v2, s32
	v_rcp_f32_e32 v3, v3
	v_mov_b32_e32 v49, v48
	s_nop 1
	v_permlane32_swap_b32_e32 v48, v49
	v_rcp_f32_e32 v0, v0
	v_min_f32_e64 v1, -v1, s32
	v_exp_f32_e32 v38, v2
	v_exp_f32_e32 v56, v1
	v_pk_mul_f32 v[36:37], v[36:37], v[6:7]
	s_waitcnt lgkmcnt(0)
	v_mul_f32_e32 v55, v8, v10
	v_pk_mul_f32 v[42:43], v[36:37], v[36:37] op_sel_hi:[0,1]
	v_mov_b32_e32 v54, v3
	v_add_f32_e32 v2, 1.0, v38
	v_mov_b32_e32 v33, v15
	v_cndmask_b32_e64 v8, 1.0, v49, s[10:11]
	v_mov_b32_e32 v14, v45
	v_mov_b32_e32 v15, v47
	v_mov_b32_e32 v45, v46
	v_pk_mul_f32 v[46:47], v[198:199], v[54:55]
	v_mov_b32_e32 v42, v0
	v_add_f32_e32 v1, 1.0, v56
	v_rcp_f32_e32 v2, v2
	v_mul_f32_e32 v55, v8, v47
	v_pk_mul_f32 v[32:33], v[32:33], v[42:43]
	v_rcp_f32_e32 v1, v1
	v_mul_f32_e32 v54, v41, v55
	v_mov_b32_e32 v41, v33
	s_nop 1
	v_permlane32_swap_b32_e32 v33, v41
	v_mov_b32_e32 v39, v48
	v_mov_b32_e32 v48, v2
	v_mul_f32_e32 v9, v9, v54
	v_pk_mul_f32 v[38:39], v[38:39], v[48:49]
	v_mul_f32_e32 v8, v40, v9
	v_mul_f32_e32 v40, v56, v1
	v_pk_mul_f32 v[48:49], v[38:39], v[46:47]
	s_waitcnt lgkmcnt(0)
	v_pk_mul_f32 v[32:33], v[32:33], v[40:41]
	v_cndmask_b32_e64 v34, 1.0, v41, s[10:11]
	v_pk_mul_f32 v[32:33], v[32:33], v[48:49]
	v_mov_b32_e32 v39, v32
	s_nop 1
	v_permlane32_swap_b32_e32 v32, v39
	v_cndmask_b32_e64 v10, 1.0, v10, s[10:11]
	v_pk_mul_f32 v[14:15], v[14:15], v[54:55]
	v_pk_mul_f32 v[8:9], v[44:45], v[8:9]
	v_cvt_pk_bf16_f32 v225, v14, v15
	s_waitcnt lgkmcnt(0)
	v_mul_f32_e32 v32, v32, v39
	v_mul_f32_e32 v197, v32, v33
	v_cndmask_b32_e64 v32, 1.0, v39, s[10:11]
	v_mul_f32_e32 v33, v32, v33
	v_mul_f32_e32 v32, v46, v33
	v_pk_mul_f32 v[2:3], v[2:3], v[32:33]
	v_mul_f32_e32 v33, v34, v49
	v_mul_f32_e32 v39, v38, v32
	v_mul_f32_e32 v32, v37, v33
	v_mul_f32_e32 v37, v36, v32
	v_mul_f32_e32 v36, v35, v37
	v_mul_f32_e32 v35, v199, v10
	v_mul_f32_e32 v38, v40, v39
	v_mul_f32_e32 v34, v13, v35
	v_pk_mul_f32 v[0:1], v[0:1], v[38:39]
	v_pk_mul_f32 v[4:5], v[4:5], v[36:37]
	v_pk_mul_f32 v[6:7], v[6:7], v[32:33]
	v_mov_b32_e32 v32, v51
	v_mov_b32_e32 v33, v53
	v_mul_f32_e32 v11, v11, v34
	v_pk_mul_f32 v[32:33], v[32:33], v[34:35]
	v_mov_b32_e32 v51, v52
	v_mul_f32_e32 v10, v12, v11
	v_cvt_pk_bf16_f32 v214, v0, v1
	v_cvt_pk_bf16_f32 v215, v2, v3
	v_cvt_pk_bf16_f32 v216, v4, v5
	v_cvt_pk_bf16_f32 v217, v6, v7
	v_pk_mul_f32 v[10:11], v[50:51], v[10:11]
	v_cvt_pk_bf16_f32 v227, v32, v33
	v_mfma_f32_32x32x16_bf16 v[48:63], v[28:31], v[214:217], v[64:79]
	v_cvt_pk_bf16_f32 v224, v8, v9
	v_cvt_pk_bf16_f32 v226, v10, v11
	v_mfma_f32_32x32x16_bf16 v[32:47], v[16:19], v[214:217], v[80:95]
	s_nop 0
	v_mfma_f32_32x32x16_bf16 v[48:63], v[24:27], v[224:227], v[48:63]
	v_mfma_f32_32x32x16_bf16 v[32:47], v[20:23], v[224:227], v[32:47]
	v_mfma_f32_32x32x16_bf16 v[16:31], v[168:171], v[214:217], v[96:111]
	v_mfma_f32_32x32x16_bf16 v[0:15], v[164:167], v[214:217], v[112:127]
	v_mfma_f32_32x32x16_bf16 v[16:31], v[172:175], v[224:227], v[16:31]
	v_mfma_f32_32x32x16_bf16 v[0:15], v[160:163], v[224:227], v[0:15]
